# scan consumer: tree-form S.a reduction (shorter serial chain) on top of decay folding
# baseline (speedup 1.0000x reference)
; #define LAS __attribute__((address_space(3)))
; DI unsigned pack2(float lo, float hi) { f32x2 v = {lo, hi}; return __builtin_bit_cast(unsigned, __builtin_convertvector(v, bf16x2_t)); }
; DI void scan_item(PP p, int l, int item, LAS unsigned char* lds) {
;     ...
;             const LAS float* sp = buf + ((c & 1) * T) * 384;
;             f32x4 Ar0, Ar1, Aw0, Aw1, Ak0, Ak1, Aa0, Aa1, Ab0, Ab1; float Avv;
;             f32x4 Br0, Br1, Bw0, Bw1, Bk0, Bk1, Ba0, Ba1, Bb0, Bb1; float Bvv;
;             SC_LD(A, sp);
;             const ptrdiff_t ystep = dir ? -512 : 512;
;             u16* Yl = Yp + (size_t)steprow(b, dir, c * T) * 512 + (ptrdiff_t)ks * ystep;
; #pragma nounroll
;             for (int st = 0; st < T; st += 2) {
;                 SC_LD(B, sp + (st + 1) * 384);
;                 SC_STEP(A, st);
;                 if (st + 2 < T) SC_LD(A, sp + (st + 2) * 384);
;                 SC_STEP(B, st + 1);
;                 if ((st & 6) == 6) {
;                     const LAS float* rp = ypl + (ks * 68 - lane) + (lane & ~7);
;                     const f32x4 q0 = *(const LAS f32x4*)rp, q1 = *(const LAS f32x4*)(rp + 4);
;                     Yl[(ptrdiff_t)(st - 6) * ystep] = (u16)(pack2(((q0[0] + q0[1]) + (q0[2] + q0[3])) + ((q1[0] + q1[1]) + (q1[2] + q1[3])), 0.f) & 0xffffu);
;                 }
.Lscan_row_done:
	s_ashr_i32 s7, s6, 31
	s_lshl_b64 s[6:7], s[6:7], 10
	v_lshl_add_u64 v[118:119], v[80:81], 0, s[6:7]
	s_lshl_b32 s8, s41, 4
	s_mov_b32 s9, s31
	v_mov_b32_e32 v126, v144
	v_mov_b32_e32 v127, v145
	v_mov_b32_e32 v124, v146
	v_mov_b32_e32 v125, v147
	v_mov_b32_e32 v122, v148
	v_mov_b32_e32 v123, v149
	v_mov_b32_e32 v120, v150
	v_mov_b32_e32 v121, v151
	ds_read_b128 v[40:43], v154 offset:1536
	ds_read_b128 v[44:47], v154 offset:1552
	ds_read_b128 v[64:67], v154 offset:2304
	ds_read_b128 v[68:71], v154 offset:2320
	ds_read_b128 v[56:59], v154 offset:2048
	ds_read_b128 v[60:63], v154 offset:2064
	ds_read_b128 v[72:75], v154 offset:2560
	ds_read_b128 v[76:79], v154 offset:2576
	ds_read_b32 v128, v153 offset:2816
	s_waitcnt lgkmcnt(9)
	v_pk_mul_f32 v[156:157], v[24:25], v[126:127]
	v_pk_mul_f32 v[90:91], v[28:29], v[122:123]
	v_pk_fma_f32 v[126:127], v[116:117], v[16:17], v[126:127] op_sel_hi:[0,1,1]
	v_pk_fma_f32 v[156:157], v[124:125], v[26:27], v[156:157]
	v_pk_fma_f32 v[90:91], v[120:121], v[30:31], v[90:91]
	v_pk_fma_f32 v[124:125], v[116:117], v[18:19], v[124:125] op_sel_hi:[0,1,1]
	v_pk_fma_f32 v[122:123], v[116:117], v[20:21], v[122:123] op_sel_hi:[0,1,1]
	v_pk_add_f32 v[156:157], v[156:157], v[90:91]
	v_pk_fma_f32 v[120:121], v[116:117], v[22:23], v[120:121] op_sel_hi:[0,1,1]
	v_add_f32_e32 v155, v156, v157
	s_nop 1
	v_add_f32_dpp v155, v155, v155 quad_perm:[1,0,3,2] row_mask:0xf bank_mask:0xf bound_ctrl:1
	s_nop 1
	v_add_f32_dpp v155, v155, v155 quad_perm:[2,3,0,1] row_mask:0xf bank_mask:0xf bound_ctrl:1
	s_nop 1
	v_add_f32_dpp v156, v155, v155 row_half_mirror row_mask:0xf bank_mask:0xf bound_ctrl:1
	v_pk_fma_f32 v[126:127], v[156:157], v[32:33], v[126:127] op_sel_hi:[0,1,1]
	v_pk_fma_f32 v[124:125], v[156:157], v[34:35], v[124:125] op_sel_hi:[0,1,1]
	v_pk_fma_f32 v[122:123], v[156:157], v[36:37], v[122:123] op_sel_hi:[0,1,1]
	v_pk_fma_f32 v[120:121], v[156:157], v[38:39], v[120:121] op_sel_hi:[0,1,1]
	ds_read_b128 v[24:27], v154 offset:3840
	ds_read_b128 v[28:31], v154 offset:3856
	ds_read_b128 v[16:19], v154 offset:3584
	ds_read_b128 v[20:23], v154 offset:3600
	ds_read_b128 v[32:35], v154 offset:4096
	ds_read_b128 v[36:39], v154 offset:4112
	ds_read_b32 v116, v153 offset:4352
	s_waitcnt lgkmcnt(7)
	v_pk_mul_f32 v[156:157], v[64:65], v[126:127]
	v_pk_mul_f32 v[90:91], v[68:69], v[122:123]
	v_pk_mul_f32 v[158:159], v[0:1], v[126:127]
	v_pk_fma_f32 v[156:157], v[124:125], v[66:67], v[156:157]
	v_pk_fma_f32 v[90:91], v[120:121], v[70:71], v[90:91]
	v_pk_fma_f32 v[158:159], v[124:125], v[2:3], v[158:159]
	v_pk_fma_f32 v[126:127], v[128:129], v[56:57], v[126:127] op_sel_hi:[0,1,1]
	v_pk_fma_f32 v[158:159], v[122:123], v[4:5], v[158:159]
	v_pk_fma_f32 v[124:125], v[128:129], v[58:59], v[124:125] op_sel_hi:[0,1,1]
	v_pk_add_f32 v[156:157], v[156:157], v[90:91]
	v_pk_fma_f32 v[158:159], v[120:121], v[6:7], v[158:159]
	v_add_f32_e32 v155, v156, v157
	v_pk_fma_f32 v[122:123], v[128:129], v[60:61], v[122:123] op_sel_hi:[0,1,1]
	v_pk_fma_f32 v[120:121], v[128:129], v[62:63], v[120:121] op_sel_hi:[0,1,1]
	ds_read_b128 v[0:3], v154 offset:3072
	ds_read_b128 v[4:7], v154 offset:3088
	v_add_f32_dpp v155, v155, v155 quad_perm:[1,0,3,2] row_mask:0xf bank_mask:0xf bound_ctrl:1
	v_add_f32_e32 v158, v158, v159
	ds_write_b32 v137, v158 offset:0
	v_add_f32_dpp v155, v155, v155 quad_perm:[2,3,0,1] row_mask:0xf bank_mask:0xf bound_ctrl:1
	s_nop 1
	v_add_f32_dpp v156, v155, v155 row_half_mirror row_mask:0xf bank_mask:0xf bound_ctrl:1
	v_pk_fma_f32 v[126:127], v[156:157], v[72:73], v[126:127] op_sel_hi:[0,1,1]
	v_pk_fma_f32 v[124:125], v[156:157], v[74:75], v[124:125] op_sel_hi:[0,1,1]
	v_pk_fma_f32 v[122:123], v[156:157], v[76:77], v[122:123] op_sel_hi:[0,1,1]
	v_pk_fma_f32 v[120:121], v[156:157], v[78:79], v[120:121] op_sel_hi:[0,1,1]
	ds_read_b128 v[64:67], v154 offset:5376
	ds_read_b128 v[68:71], v154 offset:5392
	ds_read_b128 v[56:59], v154 offset:5120
	ds_read_b128 v[60:63], v154 offset:5136
	ds_read_b128 v[72:75], v154 offset:5632
	ds_read_b128 v[76:79], v154 offset:5648
	ds_read_b32 v128, v153 offset:5888
	s_waitcnt lgkmcnt(7)
	v_pk_mul_f32 v[156:157], v[24:25], v[126:127]
	v_pk_mul_f32 v[90:91], v[28:29], v[122:123]
	v_pk_mul_f32 v[158:159], v[40:41], v[126:127]
	v_pk_fma_f32 v[156:157], v[124:125], v[26:27], v[156:157]
	v_pk_fma_f32 v[90:91], v[120:121], v[30:31], v[90:91]
	v_pk_fma_f32 v[158:159], v[124:125], v[42:43], v[158:159]
	v_pk_fma_f32 v[126:127], v[116:117], v[16:17], v[126:127] op_sel_hi:[0,1,1]
	v_pk_fma_f32 v[158:159], v[122:123], v[44:45], v[158:159]
	v_pk_fma_f32 v[124:125], v[116:117], v[18:19], v[124:125] op_sel_hi:[0,1,1]
	v_pk_add_f32 v[156:157], v[156:157], v[90:91]
	v_pk_fma_f32 v[158:159], v[120:121], v[46:47], v[158:159]
	v_add_f32_e32 v155, v156, v157
	v_pk_fma_f32 v[122:123], v[116:117], v[20:21], v[122:123] op_sel_hi:[0,1,1]
	v_pk_fma_f32 v[120:121], v[116:117], v[22:23], v[120:121] op_sel_hi:[0,1,1]
	ds_read_b128 v[40:43], v154 offset:4608
	ds_read_b128 v[44:47], v154 offset:4624
	v_add_f32_dpp v155, v155, v155 quad_perm:[1,0,3,2] row_mask:0xf bank_mask:0xf bound_ctrl:1
	v_add_f32_e32 v158, v158, v159
	ds_write_b32 v137, v158 offset:272
	v_add_f32_dpp v155, v155, v155 quad_perm:[2,3,0,1] row_mask:0xf bank_mask:0xf bound_ctrl:1
	s_nop 1
	v_add_f32_dpp v156, v155, v155 row_half_mirror row_mask:0xf bank_mask:0xf bound_ctrl:1
	v_pk_fma_f32 v[126:127], v[156:157], v[32:33], v[126:127] op_sel_hi:[0,1,1]
	v_pk_fma_f32 v[124:125], v[156:157], v[34:35], v[124:125] op_sel_hi:[0,1,1]
	v_pk_fma_f32 v[122:123], v[156:157], v[36:37], v[122:123] op_sel_hi:[0,1,1]
	v_pk_fma_f32 v[120:121], v[156:157], v[38:39], v[120:121] op_sel_hi:[0,1,1]
	ds_read_b128 v[24:27], v154 offset:6912
	ds_read_b128 v[28:31], v154 offset:6928
	ds_read_b128 v[16:19], v154 offset:6656
	ds_read_b128 v[20:23], v154 offset:6672
	ds_read_b128 v[32:35], v154 offset:7168
	ds_read_b128 v[36:39], v154 offset:7184
	ds_read_b32 v116, v153 offset:7424
	s_waitcnt lgkmcnt(7)
; #define LAS __attribute__((address_space(3)))
; DI unsigned pack2(float lo, float hi) { f32x2 v = {lo, hi}; return __builtin_bit_cast(unsigned, __builtin_convertvector(v, bf16x2_t)); }
; DI void scan_item(PP p, int l, int item, LAS unsigned char* lds) {
;     ...
;     for (int c = 0; c < NCH; ++c) {
;         if (wid >= 4) { if (c + 1 < NCH) { fill(c + 1); if (c + 2 < NCH) gl(c + 2); } }
;         else {
;             const LAS float* sp = buf + ((c & 1) * T) * 384;
;             f32x4 Ar0, Ar1, Aw0, Aw1, Ak0, Ak1, Aa0, Aa1, Ab0, Ab1; float Avv;
;             f32x4 Br0, Br1, Bw0, Bw1, Bk0, Bk1, Ba0, Ba1, Bb0, Bb1; float Bvv;
;             SC_LD(A, sp);
;             const ptrdiff_t ystep = dir ? -512 : 512;
;             u16* Yl = Yp + (size_t)steprow(b, dir, c * T) * 512 + (ptrdiff_t)ks * ystep;
; #pragma nounroll
;             for (int st = 0; st < T; st += 2) {
;                 SC_LD(B, sp + (st + 1) * 384);
;                 SC_STEP(A, st);
;                 if (st + 2 < T) SC_LD(A, sp + (st + 2) * 384);
;                 SC_STEP(B, st + 1);
;                 if ((st & 6) == 6) {
;                     const LAS float* rp = ypl + (ks * 68 - lane) + (lane & ~7);
;                     const f32x4 q0 = *(const LAS f32x4*)rp, q1 = *(const LAS f32x4*)(rp + 4);
;                     Yl[(ptrdiff_t)(st - 6) * ystep] = (u16)(pack2(((q0[0] + q0[1]) + (q0[2] + q0[3])) + ((q1[0] + q1[1]) + (q1[2] + q1[3])), 0.f) & 0xffffu);
;                 }
	v_pk_mul_f32 v[156:157], v[64:65], v[126:127]
	v_pk_mul_f32 v[90:91], v[68:69], v[122:123]
	v_pk_mul_f32 v[158:159], v[0:1], v[126:127]
	v_pk_fma_f32 v[156:157], v[124:125], v[66:67], v[156:157]
	v_pk_fma_f32 v[90:91], v[120:121], v[70:71], v[90:91]
	v_pk_fma_f32 v[158:159], v[124:125], v[2:3], v[158:159]
	v_pk_fma_f32 v[126:127], v[128:129], v[56:57], v[126:127] op_sel_hi:[0,1,1]
	v_pk_fma_f32 v[158:159], v[122:123], v[4:5], v[158:159]
	v_pk_fma_f32 v[124:125], v[128:129], v[58:59], v[124:125] op_sel_hi:[0,1,1]
	v_pk_add_f32 v[156:157], v[156:157], v[90:91]
	v_pk_fma_f32 v[158:159], v[120:121], v[6:7], v[158:159]
	v_add_f32_e32 v155, v156, v157
	v_pk_fma_f32 v[122:123], v[128:129], v[60:61], v[122:123] op_sel_hi:[0,1,1]
	v_pk_fma_f32 v[120:121], v[128:129], v[62:63], v[120:121] op_sel_hi:[0,1,1]
	ds_read_b128 v[0:3], v154 offset:6144
	ds_read_b128 v[4:7], v154 offset:6160
	v_add_f32_dpp v155, v155, v155 quad_perm:[1,0,3,2] row_mask:0xf bank_mask:0xf bound_ctrl:1
	v_add_f32_e32 v158, v158, v159
	ds_write_b32 v137, v158 offset:544
	v_add_f32_dpp v155, v155, v155 quad_perm:[2,3,0,1] row_mask:0xf bank_mask:0xf bound_ctrl:1
	s_nop 1
	v_add_f32_dpp v156, v155, v155 row_half_mirror row_mask:0xf bank_mask:0xf bound_ctrl:1
	v_pk_fma_f32 v[126:127], v[156:157], v[72:73], v[126:127] op_sel_hi:[0,1,1]
	v_pk_fma_f32 v[124:125], v[156:157], v[74:75], v[124:125] op_sel_hi:[0,1,1]
	v_pk_fma_f32 v[122:123], v[156:157], v[76:77], v[122:123] op_sel_hi:[0,1,1]
	v_pk_fma_f32 v[120:121], v[156:157], v[78:79], v[120:121] op_sel_hi:[0,1,1]
	ds_read_b128 v[64:67], v154 offset:8448
	ds_read_b128 v[68:71], v154 offset:8464
	ds_read_b128 v[56:59], v154 offset:8192
	ds_read_b128 v[60:63], v154 offset:8208
	ds_read_b128 v[72:75], v154 offset:8704
	ds_read_b128 v[76:79], v154 offset:8720
	ds_read_b32 v128, v153 offset:8960
	s_waitcnt lgkmcnt(7)
	v_pk_mul_f32 v[156:157], v[24:25], v[126:127]
	v_pk_mul_f32 v[90:91], v[28:29], v[122:123]
	v_pk_mul_f32 v[158:159], v[40:41], v[126:127]
	v_pk_fma_f32 v[156:157], v[124:125], v[26:27], v[156:157]
	v_pk_fma_f32 v[90:91], v[120:121], v[30:31], v[90:91]
	v_pk_fma_f32 v[158:159], v[124:125], v[42:43], v[158:159]
	v_pk_fma_f32 v[126:127], v[116:117], v[16:17], v[126:127] op_sel_hi:[0,1,1]
	v_pk_fma_f32 v[158:159], v[122:123], v[44:45], v[158:159]
	v_pk_fma_f32 v[124:125], v[116:117], v[18:19], v[124:125] op_sel_hi:[0,1,1]
	v_pk_add_f32 v[156:157], v[156:157], v[90:91]
	v_pk_fma_f32 v[158:159], v[120:121], v[46:47], v[158:159]
	v_add_f32_e32 v155, v156, v157
	v_pk_fma_f32 v[122:123], v[116:117], v[20:21], v[122:123] op_sel_hi:[0,1,1]
	v_pk_fma_f32 v[120:121], v[116:117], v[22:23], v[120:121] op_sel_hi:[0,1,1]
	ds_read_b128 v[40:43], v154 offset:7680
	ds_read_b128 v[44:47], v154 offset:7696
	v_add_f32_dpp v155, v155, v155 quad_perm:[1,0,3,2] row_mask:0xf bank_mask:0xf bound_ctrl:1
	v_add_f32_e32 v158, v158, v159
	ds_write_b32 v137, v158 offset:816
	v_add_f32_dpp v155, v155, v155 quad_perm:[2,3,0,1] row_mask:0xf bank_mask:0xf bound_ctrl:1
	s_nop 1
	v_add_f32_dpp v156, v155, v155 row_half_mirror row_mask:0xf bank_mask:0xf bound_ctrl:1
	v_pk_fma_f32 v[126:127], v[156:157], v[32:33], v[126:127] op_sel_hi:[0,1,1]
	v_pk_fma_f32 v[124:125], v[156:157], v[34:35], v[124:125] op_sel_hi:[0,1,1]
	v_pk_fma_f32 v[122:123], v[156:157], v[36:37], v[122:123] op_sel_hi:[0,1,1]
	v_pk_fma_f32 v[120:121], v[156:157], v[38:39], v[120:121] op_sel_hi:[0,1,1]
	ds_read_b128 v[24:27], v154 offset:9984
	ds_read_b128 v[28:31], v154 offset:10000
	ds_read_b128 v[16:19], v154 offset:9728
	ds_read_b128 v[20:23], v154 offset:9744
	ds_read_b128 v[32:35], v154 offset:10240
	ds_read_b128 v[36:39], v154 offset:10256
	ds_read_b32 v116, v153 offset:10496
	s_waitcnt lgkmcnt(7)
	v_pk_mul_f32 v[156:157], v[64:65], v[126:127]
	v_pk_mul_f32 v[90:91], v[68:69], v[122:123]
	v_pk_mul_f32 v[158:159], v[0:1], v[126:127]
	v_pk_fma_f32 v[156:157], v[124:125], v[66:67], v[156:157]
	v_pk_fma_f32 v[90:91], v[120:121], v[70:71], v[90:91]
	v_pk_fma_f32 v[158:159], v[124:125], v[2:3], v[158:159]
	v_pk_fma_f32 v[126:127], v[128:129], v[56:57], v[126:127] op_sel_hi:[0,1,1]
	v_pk_fma_f32 v[158:159], v[122:123], v[4:5], v[158:159]
	v_pk_fma_f32 v[124:125], v[128:129], v[58:59], v[124:125] op_sel_hi:[0,1,1]
	v_pk_add_f32 v[156:157], v[156:157], v[90:91]
	v_pk_fma_f32 v[158:159], v[120:121], v[6:7], v[158:159]
	v_add_f32_e32 v155, v156, v157
	v_pk_fma_f32 v[122:123], v[128:129], v[60:61], v[122:123] op_sel_hi:[0,1,1]
	v_pk_fma_f32 v[120:121], v[128:129], v[62:63], v[120:121] op_sel_hi:[0,1,1]
	ds_read_b128 v[0:3], v154 offset:9216
	ds_read_b128 v[4:7], v154 offset:9232
	v_add_f32_dpp v155, v155, v155 quad_perm:[1,0,3,2] row_mask:0xf bank_mask:0xf bound_ctrl:1
	v_add_f32_e32 v158, v158, v159
	ds_write_b32 v137, v158 offset:1088
	v_add_f32_dpp v155, v155, v155 quad_perm:[2,3,0,1] row_mask:0xf bank_mask:0xf bound_ctrl:1
	s_nop 1
	v_add_f32_dpp v156, v155, v155 row_half_mirror row_mask:0xf bank_mask:0xf bound_ctrl:1
	v_pk_fma_f32 v[126:127], v[156:157], v[72:73], v[126:127] op_sel_hi:[0,1,1]
	v_pk_fma_f32 v[124:125], v[156:157], v[74:75], v[124:125] op_sel_hi:[0,1,1]
	v_pk_fma_f32 v[122:123], v[156:157], v[76:77], v[122:123] op_sel_hi:[0,1,1]
	v_pk_fma_f32 v[120:121], v[156:157], v[78:79], v[120:121] op_sel_hi:[0,1,1]
	ds_read_b128 v[64:67], v154 offset:11520
	ds_read_b128 v[68:71], v154 offset:11536
	ds_read_b128 v[56:59], v154 offset:11264
	ds_read_b128 v[60:63], v154 offset:11280
	ds_read_b128 v[72:75], v154 offset:11776
	ds_read_b128 v[76:79], v154 offset:11792
	ds_read_b32 v128, v153 offset:12032
	ds_read_b128 v[48:51], v154 offset:11008
	ds_read_b128 v[52:55], v154 offset:11024
	s_waitcnt lgkmcnt(9)
; #define LAS __attribute__((address_space(3)))
; DI unsigned pack2(float lo, float hi) { f32x2 v = {lo, hi}; return __builtin_bit_cast(unsigned, __builtin_convertvector(v, bf16x2_t)); }
; DI void scan_item(PP p, int l, int item, LAS unsigned char* lds) {
;     ...
;     for (int c = 0; c < NCH; ++c) {
;         if (wid >= 4) { if (c + 1 < NCH) { fill(c + 1); if (c + 2 < NCH) gl(c + 2); } }
;         else {
;             const LAS float* sp = buf + ((c & 1) * T) * 384;
;             f32x4 Ar0, Ar1, Aw0, Aw1, Ak0, Ak1, Aa0, Aa1, Ab0, Ab1; float Avv;
;             f32x4 Br0, Br1, Bw0, Bw1, Bk0, Bk1, Ba0, Ba1, Bb0, Bb1; float Bvv;
;             SC_LD(A, sp);
;             const ptrdiff_t ystep = dir ? -512 : 512;
;             u16* Yl = Yp + (size_t)steprow(b, dir, c * T) * 512 + (ptrdiff_t)ks * ystep;
; #pragma nounroll
;             for (int st = 0; st < T; st += 2) {
;                 SC_LD(B, sp + (st + 1) * 384);
;                 SC_STEP(A, st);
;                 if (st + 2 < T) SC_LD(A, sp + (st + 2) * 384);
;                 SC_STEP(B, st + 1);
;                 if ((st & 6) == 6) {
;                     const LAS float* rp = ypl + (ks * 68 - lane) + (lane & ~7);
;                     const f32x4 q0 = *(const LAS f32x4*)rp, q1 = *(const LAS f32x4*)(rp + 4);
;                     Yl[(ptrdiff_t)(st - 6) * ystep] = (u16)(pack2(((q0[0] + q0[1]) + (q0[2] + q0[3])) + ((q1[0] + q1[1]) + (q1[2] + q1[3])), 0.f) & 0xffffu);
;                 }
	v_pk_mul_f32 v[156:157], v[24:25], v[126:127]
	v_pk_mul_f32 v[90:91], v[28:29], v[122:123]
	v_pk_mul_f32 v[158:159], v[40:41], v[126:127]
	v_pk_fma_f32 v[156:157], v[124:125], v[26:27], v[156:157]
	v_pk_fma_f32 v[90:91], v[120:121], v[30:31], v[90:91]
	v_pk_fma_f32 v[158:159], v[124:125], v[42:43], v[158:159]
	v_pk_fma_f32 v[126:127], v[116:117], v[16:17], v[126:127] op_sel_hi:[0,1,1]
	v_pk_fma_f32 v[158:159], v[122:123], v[44:45], v[158:159]
	v_pk_fma_f32 v[124:125], v[116:117], v[18:19], v[124:125] op_sel_hi:[0,1,1]
	v_pk_add_f32 v[156:157], v[156:157], v[90:91]
	v_pk_fma_f32 v[158:159], v[120:121], v[46:47], v[158:159]
	v_add_f32_e32 v155, v156, v157
	v_pk_fma_f32 v[122:123], v[116:117], v[20:21], v[122:123] op_sel_hi:[0,1,1]
	v_pk_fma_f32 v[120:121], v[116:117], v[22:23], v[120:121] op_sel_hi:[0,1,1]
	ds_read_b128 v[40:43], v154 offset:10752
	ds_read_b128 v[44:47], v154 offset:10768
	v_add_f32_dpp v155, v155, v155 quad_perm:[1,0,3,2] row_mask:0xf bank_mask:0xf bound_ctrl:1
	v_add_f32_e32 v158, v158, v159
	ds_write_b32 v137, v158 offset:1360
	v_add_f32_dpp v155, v155, v155 quad_perm:[2,3,0,1] row_mask:0xf bank_mask:0xf bound_ctrl:1
	s_nop 1
	v_add_f32_dpp v156, v155, v155 row_half_mirror row_mask:0xf bank_mask:0xf bound_ctrl:1
	v_pk_fma_f32 v[126:127], v[156:157], v[32:33], v[126:127] op_sel_hi:[0,1,1]
	v_pk_fma_f32 v[124:125], v[156:157], v[34:35], v[124:125] op_sel_hi:[0,1,1]
	v_pk_fma_f32 v[122:123], v[156:157], v[36:37], v[122:123] op_sel_hi:[0,1,1]
	v_pk_fma_f32 v[120:121], v[156:157], v[38:39], v[120:121] op_sel_hi:[0,1,1]
	ds_read_b128 v[24:27], v154 offset:13056
	ds_read_b128 v[28:31], v154 offset:13072
	ds_read_b128 v[16:19], v154 offset:12800
	ds_read_b128 v[20:23], v154 offset:12816
	ds_read_b128 v[32:35], v154 offset:13312
	ds_read_b128 v[36:39], v154 offset:13328
	ds_read_b32 v116, v153 offset:13568
	s_waitcnt lgkmcnt(7)
	v_pk_mul_f32 v[156:157], v[64:65], v[126:127]
	v_pk_mul_f32 v[90:91], v[68:69], v[122:123]
	v_pk_mul_f32 v[158:159], v[0:1], v[126:127]
	v_pk_fma_f32 v[156:157], v[124:125], v[66:67], v[156:157]
	v_pk_fma_f32 v[90:91], v[120:121], v[70:71], v[90:91]
	v_pk_fma_f32 v[158:159], v[124:125], v[2:3], v[158:159]
	v_pk_fma_f32 v[126:127], v[128:129], v[56:57], v[126:127] op_sel_hi:[0,1,1]
	v_pk_fma_f32 v[158:159], v[122:123], v[4:5], v[158:159]
	v_pk_fma_f32 v[124:125], v[128:129], v[58:59], v[124:125] op_sel_hi:[0,1,1]
	v_pk_add_f32 v[156:157], v[156:157], v[90:91]
	v_pk_fma_f32 v[158:159], v[120:121], v[6:7], v[158:159]
	v_add_f32_e32 v155, v156, v157
	v_pk_fma_f32 v[122:123], v[128:129], v[60:61], v[122:123] op_sel_hi:[0,1,1]
	v_pk_fma_f32 v[120:121], v[128:129], v[62:63], v[120:121] op_sel_hi:[0,1,1]
	ds_read_b128 v[0:3], v154 offset:12288
	ds_read_b128 v[4:7], v154 offset:12304
	v_add_f32_dpp v155, v155, v155 quad_perm:[1,0,3,2] row_mask:0xf bank_mask:0xf bound_ctrl:1
	v_add_f32_e32 v158, v158, v159
	ds_write_b32 v137, v158 offset:1632
	v_add_f32_dpp v155, v155, v155 quad_perm:[2,3,0,1] row_mask:0xf bank_mask:0xf bound_ctrl:1
	s_nop 1
	v_add_f32_dpp v156, v155, v155 row_half_mirror row_mask:0xf bank_mask:0xf bound_ctrl:1
	v_pk_fma_f32 v[126:127], v[156:157], v[72:73], v[126:127] op_sel_hi:[0,1,1]
	v_pk_fma_f32 v[124:125], v[156:157], v[74:75], v[124:125] op_sel_hi:[0,1,1]
	v_pk_fma_f32 v[122:123], v[156:157], v[76:77], v[122:123] op_sel_hi:[0,1,1]
	v_pk_fma_f32 v[120:121], v[156:157], v[78:79], v[120:121] op_sel_hi:[0,1,1]
	v_pk_mul_f32 v[158:159], v[40:41], v[126:127]
	s_nop 0
	v_pk_fma_f32 v[158:159], v[124:125], v[42:43], v[158:159]
	s_nop 0
	v_pk_fma_f32 v[158:159], v[122:123], v[44:45], v[158:159]
	s_nop 0
	v_pk_fma_f32 v[158:159], v[120:121], v[46:47], v[158:159]
	s_nop 0
	v_add_f32_e32 v158, v158, v159
	ds_write_b32 v137, v158 offset:1904
	ds_read_b128 v[82:85], v139
	ds_read_b128 v[86:89], v139 offset:16
	v_pk_mul_f32 v[126:127], v[48:49], v[126:127]
	v_pk_mul_f32 v[124:125], v[50:51], v[124:125]
	v_pk_mul_f32 v[122:123], v[52:53], v[122:123]
	v_pk_mul_f32 v[120:121], v[54:55], v[120:121]
	ds_read_b128 v[40:43], v154 offset:13824
	ds_read_b128 v[44:47], v154 offset:13840
	ds_read_b128 v[64:67], v154 offset:14592
	ds_read_b128 v[68:71], v154 offset:14608
	ds_read_b128 v[56:59], v154 offset:14336
	ds_read_b128 v[60:63], v154 offset:14352
	ds_read_b128 v[72:75], v154 offset:14848
	ds_read_b128 v[76:79], v154 offset:14864
	ds_read_b32 v128, v153 offset:15104
	s_waitcnt lgkmcnt(9)
	v_pk_mul_f32 v[156:157], v[24:25], v[126:127]
	v_pk_mul_f32 v[90:91], v[28:29], v[122:123]
	v_pk_fma_f32 v[126:127], v[116:117], v[16:17], v[126:127] op_sel_hi:[0,1,1]
	v_pk_fma_f32 v[156:157], v[124:125], v[26:27], v[156:157]
	v_pk_fma_f32 v[90:91], v[120:121], v[30:31], v[90:91]
	v_pk_fma_f32 v[124:125], v[116:117], v[18:19], v[124:125] op_sel_hi:[0,1,1]
	v_pk_fma_f32 v[122:123], v[116:117], v[20:21], v[122:123] op_sel_hi:[0,1,1]
	v_pk_add_f32 v[156:157], v[156:157], v[90:91]
	v_pk_fma_f32 v[120:121], v[116:117], v[22:23], v[120:121] op_sel_hi:[0,1,1]
	v_add_f32_e32 v155, v156, v157
	s_nop 1
	v_add_f32_dpp v155, v155, v155 quad_perm:[1,0,3,2] row_mask:0xf bank_mask:0xf bound_ctrl:1
	s_nop 1
	v_add_f32_dpp v155, v155, v155 quad_perm:[2,3,0,1] row_mask:0xf bank_mask:0xf bound_ctrl:1
	s_nop 1
	v_add_f32_dpp v156, v155, v155 row_half_mirror row_mask:0xf bank_mask:0xf bound_ctrl:1
	v_pk_fma_f32 v[126:127], v[156:157], v[32:33], v[126:127] op_sel_hi:[0,1,1]
	v_pk_add_f32 v[82:83], v[82:83], v[84:85]
	v_pk_fma_f32 v[124:125], v[156:157], v[34:35], v[124:125] op_sel_hi:[0,1,1]
	v_pk_add_f32 v[86:87], v[86:87], v[88:89]
	v_pk_fma_f32 v[122:123], v[156:157], v[36:37], v[122:123] op_sel_hi:[0,1,1]
	v_pk_add_f32 v[82:83], v[82:83], v[86:87]
	v_pk_fma_f32 v[120:121], v[156:157], v[38:39], v[120:121] op_sel_hi:[0,1,1]
	v_add_f32_e32 v82, v82, v83
	v_cvt_pk_bf16_f32 v82, v82, v82
	global_store_short v[118:119], v82, off
	v_lshl_add_u64 v[118:119], s[8:9], 0, v[118:119]
	ds_read_b128 v[24:27], v154 offset:16128
	ds_read_b128 v[28:31], v154 offset:16144
	ds_read_b128 v[16:19], v154 offset:15872
	ds_read_b128 v[20:23], v154 offset:15888
	ds_read_b128 v[32:35], v154 offset:16384
	ds_read_b128 v[36:39], v154 offset:16400
	ds_read_b32 v116, v153 offset:16640
	s_waitcnt lgkmcnt(7)
; #define LAS __attribute__((address_space(3)))
; DI unsigned pack2(float lo, float hi) { f32x2 v = {lo, hi}; return __builtin_bit_cast(unsigned, __builtin_convertvector(v, bf16x2_t)); }
; DI void scan_item(PP p, int l, int item, LAS unsigned char* lds) {
;     ...
;     for (int c = 0; c < NCH; ++c) {
;         if (wid >= 4) { if (c + 1 < NCH) { fill(c + 1); if (c + 2 < NCH) gl(c + 2); } }
;         else {
;             const LAS float* sp = buf + ((c & 1) * T) * 384;
;             f32x4 Ar0, Ar1, Aw0, Aw1, Ak0, Ak1, Aa0, Aa1, Ab0, Ab1; float Avv;
;             f32x4 Br0, Br1, Bw0, Bw1, Bk0, Bk1, Ba0, Ba1, Bb0, Bb1; float Bvv;
;             SC_LD(A, sp);
;             const ptrdiff_t ystep = dir ? -512 : 512;
;             u16* Yl = Yp + (size_t)steprow(b, dir, c * T) * 512 + (ptrdiff_t)ks * ystep;
; #pragma nounroll
;             for (int st = 0; st < T; st += 2) {
;                 SC_LD(B, sp + (st + 1) * 384);
;                 SC_STEP(A, st);
;                 if (st + 2 < T) SC_LD(A, sp + (st + 2) * 384);
;                 SC_STEP(B, st + 1);
;                 if ((st & 6) == 6) {
;                     const LAS float* rp = ypl + (ks * 68 - lane) + (lane & ~7);
;                     const f32x4 q0 = *(const LAS f32x4*)rp, q1 = *(const LAS f32x4*)(rp + 4);
;                     Yl[(ptrdiff_t)(st - 6) * ystep] = (u16)(pack2(((q0[0] + q0[1]) + (q0[2] + q0[3])) + ((q1[0] + q1[1]) + (q1[2] + q1[3])), 0.f) & 0xffffu);
;                 }
	v_pk_mul_f32 v[156:157], v[64:65], v[126:127]
	v_pk_mul_f32 v[90:91], v[68:69], v[122:123]
	v_pk_mul_f32 v[158:159], v[0:1], v[126:127]
	v_pk_fma_f32 v[156:157], v[124:125], v[66:67], v[156:157]
	v_pk_fma_f32 v[90:91], v[120:121], v[70:71], v[90:91]
	v_pk_fma_f32 v[158:159], v[124:125], v[2:3], v[158:159]
	v_pk_fma_f32 v[126:127], v[128:129], v[56:57], v[126:127] op_sel_hi:[0,1,1]
	v_pk_fma_f32 v[158:159], v[122:123], v[4:5], v[158:159]
	v_pk_fma_f32 v[124:125], v[128:129], v[58:59], v[124:125] op_sel_hi:[0,1,1]
	v_pk_add_f32 v[156:157], v[156:157], v[90:91]
	v_pk_fma_f32 v[158:159], v[120:121], v[6:7], v[158:159]
	v_add_f32_e32 v155, v156, v157
	v_pk_fma_f32 v[122:123], v[128:129], v[60:61], v[122:123] op_sel_hi:[0,1,1]
	v_pk_fma_f32 v[120:121], v[128:129], v[62:63], v[120:121] op_sel_hi:[0,1,1]
	ds_read_b128 v[0:3], v154 offset:15360
	ds_read_b128 v[4:7], v154 offset:15376
	v_add_f32_dpp v155, v155, v155 quad_perm:[1,0,3,2] row_mask:0xf bank_mask:0xf bound_ctrl:1
	v_add_f32_e32 v158, v158, v159
	ds_write_b32 v137, v158 offset:0
	v_add_f32_dpp v155, v155, v155 quad_perm:[2,3,0,1] row_mask:0xf bank_mask:0xf bound_ctrl:1
	s_nop 1
	v_add_f32_dpp v156, v155, v155 row_half_mirror row_mask:0xf bank_mask:0xf bound_ctrl:1
	v_pk_fma_f32 v[126:127], v[156:157], v[72:73], v[126:127] op_sel_hi:[0,1,1]
	v_pk_fma_f32 v[124:125], v[156:157], v[74:75], v[124:125] op_sel_hi:[0,1,1]
	v_pk_fma_f32 v[122:123], v[156:157], v[76:77], v[122:123] op_sel_hi:[0,1,1]
	v_pk_fma_f32 v[120:121], v[156:157], v[78:79], v[120:121] op_sel_hi:[0,1,1]
	ds_read_b128 v[64:67], v154 offset:17664
	ds_read_b128 v[68:71], v154 offset:17680
	ds_read_b128 v[56:59], v154 offset:17408
	ds_read_b128 v[60:63], v154 offset:17424
	ds_read_b128 v[72:75], v154 offset:17920
	ds_read_b128 v[76:79], v154 offset:17936
	ds_read_b32 v128, v153 offset:18176
	s_waitcnt lgkmcnt(7)
	v_pk_mul_f32 v[156:157], v[24:25], v[126:127]
	v_pk_mul_f32 v[90:91], v[28:29], v[122:123]
	v_pk_mul_f32 v[158:159], v[40:41], v[126:127]
	v_pk_fma_f32 v[156:157], v[124:125], v[26:27], v[156:157]
	v_pk_fma_f32 v[90:91], v[120:121], v[30:31], v[90:91]
	v_pk_fma_f32 v[158:159], v[124:125], v[42:43], v[158:159]
	v_pk_fma_f32 v[126:127], v[116:117], v[16:17], v[126:127] op_sel_hi:[0,1,1]
	v_pk_fma_f32 v[158:159], v[122:123], v[44:45], v[158:159]
	v_pk_fma_f32 v[124:125], v[116:117], v[18:19], v[124:125] op_sel_hi:[0,1,1]
	v_pk_add_f32 v[156:157], v[156:157], v[90:91]
	v_pk_fma_f32 v[158:159], v[120:121], v[46:47], v[158:159]
	v_add_f32_e32 v155, v156, v157
	v_pk_fma_f32 v[122:123], v[116:117], v[20:21], v[122:123] op_sel_hi:[0,1,1]
	v_pk_fma_f32 v[120:121], v[116:117], v[22:23], v[120:121] op_sel_hi:[0,1,1]
	ds_read_b128 v[40:43], v154 offset:16896
	ds_read_b128 v[44:47], v154 offset:16912
	v_add_f32_dpp v155, v155, v155 quad_perm:[1,0,3,2] row_mask:0xf bank_mask:0xf bound_ctrl:1
	v_add_f32_e32 v158, v158, v159
	ds_write_b32 v137, v158 offset:272
	v_add_f32_dpp v155, v155, v155 quad_perm:[2,3,0,1] row_mask:0xf bank_mask:0xf bound_ctrl:1
	s_nop 1
	v_add_f32_dpp v156, v155, v155 row_half_mirror row_mask:0xf bank_mask:0xf bound_ctrl:1
	v_pk_fma_f32 v[126:127], v[156:157], v[32:33], v[126:127] op_sel_hi:[0,1,1]
	v_pk_fma_f32 v[124:125], v[156:157], v[34:35], v[124:125] op_sel_hi:[0,1,1]
	v_pk_fma_f32 v[122:123], v[156:157], v[36:37], v[122:123] op_sel_hi:[0,1,1]
	v_pk_fma_f32 v[120:121], v[156:157], v[38:39], v[120:121] op_sel_hi:[0,1,1]
	ds_read_b128 v[24:27], v154 offset:19200
	ds_read_b128 v[28:31], v154 offset:19216
	ds_read_b128 v[16:19], v154 offset:18944
	ds_read_b128 v[20:23], v154 offset:18960
	ds_read_b128 v[32:35], v154 offset:19456
	ds_read_b128 v[36:39], v154 offset:19472
	ds_read_b32 v116, v153 offset:19712
	s_waitcnt lgkmcnt(7)
	v_pk_mul_f32 v[156:157], v[64:65], v[126:127]
	v_pk_mul_f32 v[90:91], v[68:69], v[122:123]
	v_pk_mul_f32 v[158:159], v[0:1], v[126:127]
	v_pk_fma_f32 v[156:157], v[124:125], v[66:67], v[156:157]
	v_pk_fma_f32 v[90:91], v[120:121], v[70:71], v[90:91]
	v_pk_fma_f32 v[158:159], v[124:125], v[2:3], v[158:159]
	v_pk_fma_f32 v[126:127], v[128:129], v[56:57], v[126:127] op_sel_hi:[0,1,1]
	v_pk_fma_f32 v[158:159], v[122:123], v[4:5], v[158:159]
	v_pk_fma_f32 v[124:125], v[128:129], v[58:59], v[124:125] op_sel_hi:[0,1,1]
	v_pk_add_f32 v[156:157], v[156:157], v[90:91]
	v_pk_fma_f32 v[158:159], v[120:121], v[6:7], v[158:159]
	v_add_f32_e32 v155, v156, v157
	v_pk_fma_f32 v[122:123], v[128:129], v[60:61], v[122:123] op_sel_hi:[0,1,1]
	v_pk_fma_f32 v[120:121], v[128:129], v[62:63], v[120:121] op_sel_hi:[0,1,1]
	ds_read_b128 v[0:3], v154 offset:18432
	ds_read_b128 v[4:7], v154 offset:18448
	v_add_f32_dpp v155, v155, v155 quad_perm:[1,0,3,2] row_mask:0xf bank_mask:0xf bound_ctrl:1
	v_add_f32_e32 v158, v158, v159
	ds_write_b32 v137, v158 offset:544
	v_add_f32_dpp v155, v155, v155 quad_perm:[2,3,0,1] row_mask:0xf bank_mask:0xf bound_ctrl:1
	s_nop 1
	v_add_f32_dpp v156, v155, v155 row_half_mirror row_mask:0xf bank_mask:0xf bound_ctrl:1
	v_pk_fma_f32 v[126:127], v[156:157], v[72:73], v[126:127] op_sel_hi:[0,1,1]
	v_pk_fma_f32 v[124:125], v[156:157], v[74:75], v[124:125] op_sel_hi:[0,1,1]
	v_pk_fma_f32 v[122:123], v[156:157], v[76:77], v[122:123] op_sel_hi:[0,1,1]
	v_pk_fma_f32 v[120:121], v[156:157], v[78:79], v[120:121] op_sel_hi:[0,1,1]
	ds_read_b128 v[64:67], v154 offset:20736
	ds_read_b128 v[68:71], v154 offset:20752
	ds_read_b128 v[56:59], v154 offset:20480
	ds_read_b128 v[60:63], v154 offset:20496
	ds_read_b128 v[72:75], v154 offset:20992
	ds_read_b128 v[76:79], v154 offset:21008
	ds_read_b32 v128, v153 offset:21248
	s_waitcnt lgkmcnt(7)
; #define LAS __attribute__((address_space(3)))
; DI unsigned pack2(float lo, float hi) { f32x2 v = {lo, hi}; return __builtin_bit_cast(unsigned, __builtin_convertvector(v, bf16x2_t)); }
; DI void scan_item(PP p, int l, int item, LAS unsigned char* lds) {
;     ...
;     for (int c = 0; c < NCH; ++c) {
;         if (wid >= 4) { if (c + 1 < NCH) { fill(c + 1); if (c + 2 < NCH) gl(c + 2); } }
;         else {
;             const LAS float* sp = buf + ((c & 1) * T) * 384;
;             f32x4 Ar0, Ar1, Aw0, Aw1, Ak0, Ak1, Aa0, Aa1, Ab0, Ab1; float Avv;
;             f32x4 Br0, Br1, Bw0, Bw1, Bk0, Bk1, Ba0, Ba1, Bb0, Bb1; float Bvv;
;             SC_LD(A, sp);
;             const ptrdiff_t ystep = dir ? -512 : 512;
;             u16* Yl = Yp + (size_t)steprow(b, dir, c * T) * 512 + (ptrdiff_t)ks * ystep;
; #pragma nounroll
;             for (int st = 0; st < T; st += 2) {
;                 SC_LD(B, sp + (st + 1) * 384);
;                 SC_STEP(A, st);
;                 if (st + 2 < T) SC_LD(A, sp + (st + 2) * 384);
;                 SC_STEP(B, st + 1);
;                 if ((st & 6) == 6) {
;                     const LAS float* rp = ypl + (ks * 68 - lane) + (lane & ~7);
;                     const f32x4 q0 = *(const LAS f32x4*)rp, q1 = *(const LAS f32x4*)(rp + 4);
;                     Yl[(ptrdiff_t)(st - 6) * ystep] = (u16)(pack2(((q0[0] + q0[1]) + (q0[2] + q0[3])) + ((q1[0] + q1[1]) + (q1[2] + q1[3])), 0.f) & 0xffffu);
;                 }
	v_pk_mul_f32 v[156:157], v[24:25], v[126:127]
	v_pk_mul_f32 v[90:91], v[28:29], v[122:123]
	v_pk_mul_f32 v[158:159], v[40:41], v[126:127]
	v_pk_fma_f32 v[156:157], v[124:125], v[26:27], v[156:157]
	v_pk_fma_f32 v[90:91], v[120:121], v[30:31], v[90:91]
	v_pk_fma_f32 v[158:159], v[124:125], v[42:43], v[158:159]
	v_pk_fma_f32 v[126:127], v[116:117], v[16:17], v[126:127] op_sel_hi:[0,1,1]
	v_pk_fma_f32 v[158:159], v[122:123], v[44:45], v[158:159]
	v_pk_fma_f32 v[124:125], v[116:117], v[18:19], v[124:125] op_sel_hi:[0,1,1]
	v_pk_add_f32 v[156:157], v[156:157], v[90:91]
	v_pk_fma_f32 v[158:159], v[120:121], v[46:47], v[158:159]
	v_add_f32_e32 v155, v156, v157
	v_pk_fma_f32 v[122:123], v[116:117], v[20:21], v[122:123] op_sel_hi:[0,1,1]
	v_pk_fma_f32 v[120:121], v[116:117], v[22:23], v[120:121] op_sel_hi:[0,1,1]
	ds_read_b128 v[40:43], v154 offset:19968
	ds_read_b128 v[44:47], v154 offset:19984
	v_add_f32_dpp v155, v155, v155 quad_perm:[1,0,3,2] row_mask:0xf bank_mask:0xf bound_ctrl:1
	v_add_f32_e32 v158, v158, v159
	ds_write_b32 v137, v158 offset:816
	v_add_f32_dpp v155, v155, v155 quad_perm:[2,3,0,1] row_mask:0xf bank_mask:0xf bound_ctrl:1
	s_nop 1
	v_add_f32_dpp v156, v155, v155 row_half_mirror row_mask:0xf bank_mask:0xf bound_ctrl:1
	v_pk_fma_f32 v[126:127], v[156:157], v[32:33], v[126:127] op_sel_hi:[0,1,1]
	v_pk_fma_f32 v[124:125], v[156:157], v[34:35], v[124:125] op_sel_hi:[0,1,1]
	v_pk_fma_f32 v[122:123], v[156:157], v[36:37], v[122:123] op_sel_hi:[0,1,1]
	v_pk_fma_f32 v[120:121], v[156:157], v[38:39], v[120:121] op_sel_hi:[0,1,1]
	ds_read_b128 v[24:27], v154 offset:22272
	ds_read_b128 v[28:31], v154 offset:22288
	ds_read_b128 v[16:19], v154 offset:22016
	ds_read_b128 v[20:23], v154 offset:22032
	ds_read_b128 v[32:35], v154 offset:22528
	ds_read_b128 v[36:39], v154 offset:22544
	ds_read_b32 v116, v153 offset:22784
	s_waitcnt lgkmcnt(7)
	v_pk_mul_f32 v[156:157], v[64:65], v[126:127]
	v_pk_mul_f32 v[90:91], v[68:69], v[122:123]
	v_pk_mul_f32 v[158:159], v[0:1], v[126:127]
	v_pk_fma_f32 v[156:157], v[124:125], v[66:67], v[156:157]
	v_pk_fma_f32 v[90:91], v[120:121], v[70:71], v[90:91]
	v_pk_fma_f32 v[158:159], v[124:125], v[2:3], v[158:159]
	v_pk_fma_f32 v[126:127], v[128:129], v[56:57], v[126:127] op_sel_hi:[0,1,1]
	v_pk_fma_f32 v[158:159], v[122:123], v[4:5], v[158:159]
	v_pk_fma_f32 v[124:125], v[128:129], v[58:59], v[124:125] op_sel_hi:[0,1,1]
	v_pk_add_f32 v[156:157], v[156:157], v[90:91]
	v_pk_fma_f32 v[158:159], v[120:121], v[6:7], v[158:159]
	v_add_f32_e32 v155, v156, v157
	v_pk_fma_f32 v[122:123], v[128:129], v[60:61], v[122:123] op_sel_hi:[0,1,1]
	v_pk_fma_f32 v[120:121], v[128:129], v[62:63], v[120:121] op_sel_hi:[0,1,1]
	ds_read_b128 v[0:3], v154 offset:21504
	ds_read_b128 v[4:7], v154 offset:21520
	v_add_f32_dpp v155, v155, v155 quad_perm:[1,0,3,2] row_mask:0xf bank_mask:0xf bound_ctrl:1
	v_add_f32_e32 v158, v158, v159
	ds_write_b32 v137, v158 offset:1088
	v_add_f32_dpp v155, v155, v155 quad_perm:[2,3,0,1] row_mask:0xf bank_mask:0xf bound_ctrl:1
	s_nop 1
	v_add_f32_dpp v156, v155, v155 row_half_mirror row_mask:0xf bank_mask:0xf bound_ctrl:1
	v_pk_fma_f32 v[126:127], v[156:157], v[72:73], v[126:127] op_sel_hi:[0,1,1]
	v_pk_fma_f32 v[124:125], v[156:157], v[74:75], v[124:125] op_sel_hi:[0,1,1]
	v_pk_fma_f32 v[122:123], v[156:157], v[76:77], v[122:123] op_sel_hi:[0,1,1]
	v_pk_fma_f32 v[120:121], v[156:157], v[78:79], v[120:121] op_sel_hi:[0,1,1]
	ds_read_b128 v[64:67], v154 offset:23808
	ds_read_b128 v[68:71], v154 offset:23824
	ds_read_b128 v[56:59], v154 offset:23552
	ds_read_b128 v[60:63], v154 offset:23568
	ds_read_b128 v[72:75], v154 offset:24064
	ds_read_b128 v[76:79], v154 offset:24080
	ds_read_b32 v128, v153 offset:24320
	ds_read_b128 v[48:51], v154 offset:23296
	ds_read_b128 v[52:55], v154 offset:23312
	s_waitcnt lgkmcnt(9)
	v_pk_mul_f32 v[156:157], v[24:25], v[126:127]
	v_pk_mul_f32 v[90:91], v[28:29], v[122:123]
	v_pk_mul_f32 v[158:159], v[40:41], v[126:127]
	v_pk_fma_f32 v[156:157], v[124:125], v[26:27], v[156:157]
	v_pk_fma_f32 v[90:91], v[120:121], v[30:31], v[90:91]
	v_pk_fma_f32 v[158:159], v[124:125], v[42:43], v[158:159]
	v_pk_fma_f32 v[126:127], v[116:117], v[16:17], v[126:127] op_sel_hi:[0,1,1]
	v_pk_fma_f32 v[158:159], v[122:123], v[44:45], v[158:159]
	v_pk_fma_f32 v[124:125], v[116:117], v[18:19], v[124:125] op_sel_hi:[0,1,1]
	v_pk_add_f32 v[156:157], v[156:157], v[90:91]
	v_pk_fma_f32 v[158:159], v[120:121], v[46:47], v[158:159]
	v_add_f32_e32 v155, v156, v157
	v_pk_fma_f32 v[122:123], v[116:117], v[20:21], v[122:123] op_sel_hi:[0,1,1]
	v_pk_fma_f32 v[120:121], v[116:117], v[22:23], v[120:121] op_sel_hi:[0,1,1]
	ds_read_b128 v[40:43], v154 offset:23040
	ds_read_b128 v[44:47], v154 offset:23056
	v_add_f32_dpp v155, v155, v155 quad_perm:[1,0,3,2] row_mask:0xf bank_mask:0xf bound_ctrl:1
	v_add_f32_e32 v158, v158, v159
	ds_write_b32 v137, v158 offset:1360
	v_add_f32_dpp v155, v155, v155 quad_perm:[2,3,0,1] row_mask:0xf bank_mask:0xf bound_ctrl:1
	s_nop 1
	v_add_f32_dpp v156, v155, v155 row_half_mirror row_mask:0xf bank_mask:0xf bound_ctrl:1
	v_pk_fma_f32 v[126:127], v[156:157], v[32:33], v[126:127] op_sel_hi:[0,1,1]
	v_pk_fma_f32 v[124:125], v[156:157], v[34:35], v[124:125] op_sel_hi:[0,1,1]
	v_pk_fma_f32 v[122:123], v[156:157], v[36:37], v[122:123] op_sel_hi:[0,1,1]
	v_pk_fma_f32 v[120:121], v[156:157], v[38:39], v[120:121] op_sel_hi:[0,1,1]
	ds_read_b128 v[24:27], v154 offset:25344
	ds_read_b128 v[28:31], v154 offset:25360
	ds_read_b128 v[16:19], v154 offset:25088
	ds_read_b128 v[20:23], v154 offset:25104
	ds_read_b128 v[32:35], v154 offset:25600
	ds_read_b128 v[36:39], v154 offset:25616
	ds_read_b32 v116, v153 offset:25856
	s_waitcnt lgkmcnt(7)
; #define LAS __attribute__((address_space(3)))
; DI unsigned pack2(float lo, float hi) { f32x2 v = {lo, hi}; return __builtin_bit_cast(unsigned, __builtin_convertvector(v, bf16x2_t)); }
; DI void scan_item(PP p, int l, int item, LAS unsigned char* lds) {
;     ...
;     for (int c = 0; c < NCH; ++c) {
;         if (wid >= 4) { if (c + 1 < NCH) { fill(c + 1); if (c + 2 < NCH) gl(c + 2); } }
;         else {
;             const LAS float* sp = buf + ((c & 1) * T) * 384;
;             f32x4 Ar0, Ar1, Aw0, Aw1, Ak0, Ak1, Aa0, Aa1, Ab0, Ab1; float Avv;
;             f32x4 Br0, Br1, Bw0, Bw1, Bk0, Bk1, Ba0, Ba1, Bb0, Bb1; float Bvv;
;             SC_LD(A, sp);
;             const ptrdiff_t ystep = dir ? -512 : 512;
;             u16* Yl = Yp + (size_t)steprow(b, dir, c * T) * 512 + (ptrdiff_t)ks * ystep;
; #pragma nounroll
;             for (int st = 0; st < T; st += 2) {
;                 SC_LD(B, sp + (st + 1) * 384);
;                 SC_STEP(A, st);
;                 if (st + 2 < T) SC_LD(A, sp + (st + 2) * 384);
;                 SC_STEP(B, st + 1);
;                 if ((st & 6) == 6) {
;                     const LAS float* rp = ypl + (ks * 68 - lane) + (lane & ~7);
;                     const f32x4 q0 = *(const LAS f32x4*)rp, q1 = *(const LAS f32x4*)(rp + 4);
;                     Yl[(ptrdiff_t)(st - 6) * ystep] = (u16)(pack2(((q0[0] + q0[1]) + (q0[2] + q0[3])) + ((q1[0] + q1[1]) + (q1[2] + q1[3])), 0.f) & 0xffffu);
;                 }
	v_pk_mul_f32 v[156:157], v[64:65], v[126:127]
	v_pk_mul_f32 v[90:91], v[68:69], v[122:123]
	v_pk_mul_f32 v[158:159], v[0:1], v[126:127]
	v_pk_fma_f32 v[156:157], v[124:125], v[66:67], v[156:157]
	v_pk_fma_f32 v[90:91], v[120:121], v[70:71], v[90:91]
	v_pk_fma_f32 v[158:159], v[124:125], v[2:3], v[158:159]
	v_pk_fma_f32 v[126:127], v[128:129], v[56:57], v[126:127] op_sel_hi:[0,1,1]
	v_pk_fma_f32 v[158:159], v[122:123], v[4:5], v[158:159]
	v_pk_fma_f32 v[124:125], v[128:129], v[58:59], v[124:125] op_sel_hi:[0,1,1]
	v_pk_add_f32 v[156:157], v[156:157], v[90:91]
	v_pk_fma_f32 v[158:159], v[120:121], v[6:7], v[158:159]
	v_add_f32_e32 v155, v156, v157
	v_pk_fma_f32 v[122:123], v[128:129], v[60:61], v[122:123] op_sel_hi:[0,1,1]
	v_pk_fma_f32 v[120:121], v[128:129], v[62:63], v[120:121] op_sel_hi:[0,1,1]
	ds_read_b128 v[0:3], v154 offset:24576
	ds_read_b128 v[4:7], v154 offset:24592
	v_add_f32_dpp v155, v155, v155 quad_perm:[1,0,3,2] row_mask:0xf bank_mask:0xf bound_ctrl:1
	v_add_f32_e32 v158, v158, v159
	ds_write_b32 v137, v158 offset:1632
	v_add_f32_dpp v155, v155, v155 quad_perm:[2,3,0,1] row_mask:0xf bank_mask:0xf bound_ctrl:1
	s_nop 1
	v_add_f32_dpp v156, v155, v155 row_half_mirror row_mask:0xf bank_mask:0xf bound_ctrl:1
	v_pk_fma_f32 v[126:127], v[156:157], v[72:73], v[126:127] op_sel_hi:[0,1,1]
	v_pk_fma_f32 v[124:125], v[156:157], v[74:75], v[124:125] op_sel_hi:[0,1,1]
	v_pk_fma_f32 v[122:123], v[156:157], v[76:77], v[122:123] op_sel_hi:[0,1,1]
	v_pk_fma_f32 v[120:121], v[156:157], v[78:79], v[120:121] op_sel_hi:[0,1,1]
	v_pk_mul_f32 v[158:159], v[40:41], v[126:127]
	s_nop 0
	v_pk_fma_f32 v[158:159], v[124:125], v[42:43], v[158:159]
	s_nop 0
	v_pk_fma_f32 v[158:159], v[122:123], v[44:45], v[158:159]
	s_nop 0
	v_pk_fma_f32 v[158:159], v[120:121], v[46:47], v[158:159]
	s_nop 0
	v_add_f32_e32 v158, v158, v159
	ds_write_b32 v137, v158 offset:1904
	ds_read_b128 v[82:85], v139
	ds_read_b128 v[86:89], v139 offset:16
	v_pk_mul_f32 v[126:127], v[48:49], v[126:127]
	v_pk_mul_f32 v[124:125], v[50:51], v[124:125]
	v_pk_mul_f32 v[122:123], v[52:53], v[122:123]
	v_pk_mul_f32 v[120:121], v[54:55], v[120:121]
	ds_read_b128 v[40:43], v154 offset:26112
	ds_read_b128 v[44:47], v154 offset:26128
	ds_read_b128 v[64:67], v154 offset:26880
	ds_read_b128 v[68:71], v154 offset:26896
	ds_read_b128 v[56:59], v154 offset:26624
	ds_read_b128 v[60:63], v154 offset:26640
	ds_read_b128 v[72:75], v154 offset:27136
	ds_read_b128 v[76:79], v154 offset:27152
	ds_read_b32 v128, v153 offset:27392
	s_waitcnt lgkmcnt(9)
	v_pk_mul_f32 v[156:157], v[24:25], v[126:127]
	v_pk_mul_f32 v[90:91], v[28:29], v[122:123]
	v_pk_fma_f32 v[126:127], v[116:117], v[16:17], v[126:127] op_sel_hi:[0,1,1]
	v_pk_fma_f32 v[156:157], v[124:125], v[26:27], v[156:157]
	v_pk_fma_f32 v[90:91], v[120:121], v[30:31], v[90:91]
	v_pk_fma_f32 v[124:125], v[116:117], v[18:19], v[124:125] op_sel_hi:[0,1,1]
	v_pk_fma_f32 v[122:123], v[116:117], v[20:21], v[122:123] op_sel_hi:[0,1,1]
	v_pk_add_f32 v[156:157], v[156:157], v[90:91]
	v_pk_fma_f32 v[120:121], v[116:117], v[22:23], v[120:121] op_sel_hi:[0,1,1]
	v_add_f32_e32 v155, v156, v157
	s_nop 1
	v_add_f32_dpp v155, v155, v155 quad_perm:[1,0,3,2] row_mask:0xf bank_mask:0xf bound_ctrl:1
	s_nop 1
	v_add_f32_dpp v155, v155, v155 quad_perm:[2,3,0,1] row_mask:0xf bank_mask:0xf bound_ctrl:1
	s_nop 1
	v_add_f32_dpp v156, v155, v155 row_half_mirror row_mask:0xf bank_mask:0xf bound_ctrl:1
	v_pk_fma_f32 v[126:127], v[156:157], v[32:33], v[126:127] op_sel_hi:[0,1,1]
	v_pk_add_f32 v[82:83], v[82:83], v[84:85]
	v_pk_fma_f32 v[124:125], v[156:157], v[34:35], v[124:125] op_sel_hi:[0,1,1]
	v_pk_add_f32 v[86:87], v[86:87], v[88:89]
	v_pk_fma_f32 v[122:123], v[156:157], v[36:37], v[122:123] op_sel_hi:[0,1,1]
	v_pk_add_f32 v[82:83], v[82:83], v[86:87]
	v_pk_fma_f32 v[120:121], v[156:157], v[38:39], v[120:121] op_sel_hi:[0,1,1]
	v_add_f32_e32 v82, v82, v83
	v_cvt_pk_bf16_f32 v82, v82, v82
	global_store_short v[118:119], v82, off
	v_lshl_add_u64 v[118:119], s[8:9], 0, v[118:119]
	ds_read_b128 v[24:27], v154 offset:28416
	ds_read_b128 v[28:31], v154 offset:28432
	ds_read_b128 v[16:19], v154 offset:28160
	ds_read_b128 v[20:23], v154 offset:28176
	ds_read_b128 v[32:35], v154 offset:28672
	ds_read_b128 v[36:39], v154 offset:28688
	ds_read_b32 v116, v153 offset:28928
	s_waitcnt lgkmcnt(7)
	v_pk_mul_f32 v[156:157], v[64:65], v[126:127]
	v_pk_mul_f32 v[90:91], v[68:69], v[122:123]
	v_pk_mul_f32 v[158:159], v[0:1], v[126:127]
	v_pk_fma_f32 v[156:157], v[124:125], v[66:67], v[156:157]
	v_pk_fma_f32 v[90:91], v[120:121], v[70:71], v[90:91]
	v_pk_fma_f32 v[158:159], v[124:125], v[2:3], v[158:159]
	v_pk_fma_f32 v[126:127], v[128:129], v[56:57], v[126:127] op_sel_hi:[0,1,1]
	v_pk_fma_f32 v[158:159], v[122:123], v[4:5], v[158:159]
	v_pk_fma_f32 v[124:125], v[128:129], v[58:59], v[124:125] op_sel_hi:[0,1,1]
	v_pk_add_f32 v[156:157], v[156:157], v[90:91]
	v_pk_fma_f32 v[158:159], v[120:121], v[6:7], v[158:159]
	v_add_f32_e32 v155, v156, v157
	v_pk_fma_f32 v[122:123], v[128:129], v[60:61], v[122:123] op_sel_hi:[0,1,1]
	v_pk_fma_f32 v[120:121], v[128:129], v[62:63], v[120:121] op_sel_hi:[0,1,1]
	ds_read_b128 v[0:3], v154 offset:27648
	ds_read_b128 v[4:7], v154 offset:27664
	v_add_f32_dpp v155, v155, v155 quad_perm:[1,0,3,2] row_mask:0xf bank_mask:0xf bound_ctrl:1
	v_add_f32_e32 v158, v158, v159
	ds_write_b32 v137, v158 offset:0
	v_add_f32_dpp v155, v155, v155 quad_perm:[2,3,0,1] row_mask:0xf bank_mask:0xf bound_ctrl:1
	s_nop 1
	v_add_f32_dpp v156, v155, v155 row_half_mirror row_mask:0xf bank_mask:0xf bound_ctrl:1
	v_pk_fma_f32 v[126:127], v[156:157], v[72:73], v[126:127] op_sel_hi:[0,1,1]
	v_pk_fma_f32 v[124:125], v[156:157], v[74:75], v[124:125] op_sel_hi:[0,1,1]
	v_pk_fma_f32 v[122:123], v[156:157], v[76:77], v[122:123] op_sel_hi:[0,1,1]
	v_pk_fma_f32 v[120:121], v[156:157], v[78:79], v[120:121] op_sel_hi:[0,1,1]
	ds_read_b128 v[64:67], v154 offset:29952
	ds_read_b128 v[68:71], v154 offset:29968
	ds_read_b128 v[56:59], v154 offset:29696
	ds_read_b128 v[60:63], v154 offset:29712
	ds_read_b128 v[72:75], v154 offset:30208
	ds_read_b128 v[76:79], v154 offset:30224
	ds_read_b32 v128, v153 offset:30464
	s_waitcnt lgkmcnt(7)
; #define LAS __attribute__((address_space(3)))
; DI unsigned pack2(float lo, float hi) { f32x2 v = {lo, hi}; return __builtin_bit_cast(unsigned, __builtin_convertvector(v, bf16x2_t)); }
; DI void scan_item(PP p, int l, int item, LAS unsigned char* lds) {
;     ...
;     for (int c = 0; c < NCH; ++c) {
;         if (wid >= 4) { if (c + 1 < NCH) { fill(c + 1); if (c + 2 < NCH) gl(c + 2); } }
;         else {
;             const LAS float* sp = buf + ((c & 1) * T) * 384;
;             f32x4 Ar0, Ar1, Aw0, Aw1, Ak0, Ak1, Aa0, Aa1, Ab0, Ab1; float Avv;
;             f32x4 Br0, Br1, Bw0, Bw1, Bk0, Bk1, Ba0, Ba1, Bb0, Bb1; float Bvv;
;             SC_LD(A, sp);
;             const ptrdiff_t ystep = dir ? -512 : 512;
;             u16* Yl = Yp + (size_t)steprow(b, dir, c * T) * 512 + (ptrdiff_t)ks * ystep;
; #pragma nounroll
;             for (int st = 0; st < T; st += 2) {
;                 SC_LD(B, sp + (st + 1) * 384);
;                 SC_STEP(A, st);
;                 if (st + 2 < T) SC_LD(A, sp + (st + 2) * 384);
;                 SC_STEP(B, st + 1);
;                 if ((st & 6) == 6) {
;                     const LAS float* rp = ypl + (ks * 68 - lane) + (lane & ~7);
;                     const f32x4 q0 = *(const LAS f32x4*)rp, q1 = *(const LAS f32x4*)(rp + 4);
;                     Yl[(ptrdiff_t)(st - 6) * ystep] = (u16)(pack2(((q0[0] + q0[1]) + (q0[2] + q0[3])) + ((q1[0] + q1[1]) + (q1[2] + q1[3])), 0.f) & 0xffffu);
;                 }
	v_pk_mul_f32 v[156:157], v[24:25], v[126:127]
	v_pk_mul_f32 v[90:91], v[28:29], v[122:123]
	v_pk_mul_f32 v[158:159], v[40:41], v[126:127]
	v_pk_fma_f32 v[156:157], v[124:125], v[26:27], v[156:157]
	v_pk_fma_f32 v[90:91], v[120:121], v[30:31], v[90:91]
	v_pk_fma_f32 v[158:159], v[124:125], v[42:43], v[158:159]
	v_pk_fma_f32 v[126:127], v[116:117], v[16:17], v[126:127] op_sel_hi:[0,1,1]
	v_pk_fma_f32 v[158:159], v[122:123], v[44:45], v[158:159]
	v_pk_fma_f32 v[124:125], v[116:117], v[18:19], v[124:125] op_sel_hi:[0,1,1]
	v_pk_add_f32 v[156:157], v[156:157], v[90:91]
	v_pk_fma_f32 v[158:159], v[120:121], v[46:47], v[158:159]
	v_add_f32_e32 v155, v156, v157
	v_pk_fma_f32 v[122:123], v[116:117], v[20:21], v[122:123] op_sel_hi:[0,1,1]
	v_pk_fma_f32 v[120:121], v[116:117], v[22:23], v[120:121] op_sel_hi:[0,1,1]
	ds_read_b128 v[40:43], v154 offset:29184
	ds_read_b128 v[44:47], v154 offset:29200
	v_add_f32_dpp v155, v155, v155 quad_perm:[1,0,3,2] row_mask:0xf bank_mask:0xf bound_ctrl:1
	v_add_f32_e32 v158, v158, v159
	ds_write_b32 v137, v158 offset:272
	v_add_f32_dpp v155, v155, v155 quad_perm:[2,3,0,1] row_mask:0xf bank_mask:0xf bound_ctrl:1
	s_nop 1
	v_add_f32_dpp v156, v155, v155 row_half_mirror row_mask:0xf bank_mask:0xf bound_ctrl:1
	v_pk_fma_f32 v[126:127], v[156:157], v[32:33], v[126:127] op_sel_hi:[0,1,1]
	v_pk_fma_f32 v[124:125], v[156:157], v[34:35], v[124:125] op_sel_hi:[0,1,1]
	v_pk_fma_f32 v[122:123], v[156:157], v[36:37], v[122:123] op_sel_hi:[0,1,1]
	v_pk_fma_f32 v[120:121], v[156:157], v[38:39], v[120:121] op_sel_hi:[0,1,1]
	ds_read_b128 v[24:27], v154 offset:31488
	ds_read_b128 v[28:31], v154 offset:31504
	ds_read_b128 v[16:19], v154 offset:31232
	ds_read_b128 v[20:23], v154 offset:31248
	ds_read_b128 v[32:35], v154 offset:31744
	ds_read_b128 v[36:39], v154 offset:31760
	ds_read_b32 v116, v153 offset:32000
	s_waitcnt lgkmcnt(7)
	v_pk_mul_f32 v[156:157], v[64:65], v[126:127]
	v_pk_mul_f32 v[90:91], v[68:69], v[122:123]
	v_pk_mul_f32 v[158:159], v[0:1], v[126:127]
	v_pk_fma_f32 v[156:157], v[124:125], v[66:67], v[156:157]
	v_pk_fma_f32 v[90:91], v[120:121], v[70:71], v[90:91]
	v_pk_fma_f32 v[158:159], v[124:125], v[2:3], v[158:159]
	v_pk_fma_f32 v[126:127], v[128:129], v[56:57], v[126:127] op_sel_hi:[0,1,1]
	v_pk_fma_f32 v[158:159], v[122:123], v[4:5], v[158:159]
	v_pk_fma_f32 v[124:125], v[128:129], v[58:59], v[124:125] op_sel_hi:[0,1,1]
	v_pk_add_f32 v[156:157], v[156:157], v[90:91]
	v_pk_fma_f32 v[158:159], v[120:121], v[6:7], v[158:159]
	v_add_f32_e32 v155, v156, v157
	v_pk_fma_f32 v[122:123], v[128:129], v[60:61], v[122:123] op_sel_hi:[0,1,1]
	v_pk_fma_f32 v[120:121], v[128:129], v[62:63], v[120:121] op_sel_hi:[0,1,1]
	ds_read_b128 v[0:3], v154 offset:30720
	ds_read_b128 v[4:7], v154 offset:30736
	v_add_f32_dpp v155, v155, v155 quad_perm:[1,0,3,2] row_mask:0xf bank_mask:0xf bound_ctrl:1
	v_add_f32_e32 v158, v158, v159
	ds_write_b32 v137, v158 offset:544
	v_add_f32_dpp v155, v155, v155 quad_perm:[2,3,0,1] row_mask:0xf bank_mask:0xf bound_ctrl:1
	s_nop 1
	v_add_f32_dpp v156, v155, v155 row_half_mirror row_mask:0xf bank_mask:0xf bound_ctrl:1
	v_pk_fma_f32 v[126:127], v[156:157], v[72:73], v[126:127] op_sel_hi:[0,1,1]
	v_pk_fma_f32 v[124:125], v[156:157], v[74:75], v[124:125] op_sel_hi:[0,1,1]
	v_pk_fma_f32 v[122:123], v[156:157], v[76:77], v[122:123] op_sel_hi:[0,1,1]
	v_pk_fma_f32 v[120:121], v[156:157], v[78:79], v[120:121] op_sel_hi:[0,1,1]
	ds_read_b128 v[64:67], v154 offset:33024
	ds_read_b128 v[68:71], v154 offset:33040
	ds_read_b128 v[56:59], v154 offset:32768
	ds_read_b128 v[60:63], v154 offset:32784
	ds_read_b128 v[72:75], v154 offset:33280
	ds_read_b128 v[76:79], v154 offset:33296
	ds_read_b32 v128, v153 offset:33536
	s_waitcnt lgkmcnt(7)
	v_pk_mul_f32 v[156:157], v[24:25], v[126:127]
	v_pk_mul_f32 v[90:91], v[28:29], v[122:123]
	v_pk_mul_f32 v[158:159], v[40:41], v[126:127]
	v_pk_fma_f32 v[156:157], v[124:125], v[26:27], v[156:157]
	v_pk_fma_f32 v[90:91], v[120:121], v[30:31], v[90:91]
	v_pk_fma_f32 v[158:159], v[124:125], v[42:43], v[158:159]
	v_pk_fma_f32 v[126:127], v[116:117], v[16:17], v[126:127] op_sel_hi:[0,1,1]
	v_pk_fma_f32 v[158:159], v[122:123], v[44:45], v[158:159]
	v_pk_fma_f32 v[124:125], v[116:117], v[18:19], v[124:125] op_sel_hi:[0,1,1]
	v_pk_add_f32 v[156:157], v[156:157], v[90:91]
	v_pk_fma_f32 v[158:159], v[120:121], v[46:47], v[158:159]
	v_add_f32_e32 v155, v156, v157
	v_pk_fma_f32 v[122:123], v[116:117], v[20:21], v[122:123] op_sel_hi:[0,1,1]
	v_pk_fma_f32 v[120:121], v[116:117], v[22:23], v[120:121] op_sel_hi:[0,1,1]
	ds_read_b128 v[40:43], v154 offset:32256
	ds_read_b128 v[44:47], v154 offset:32272
	v_add_f32_dpp v155, v155, v155 quad_perm:[1,0,3,2] row_mask:0xf bank_mask:0xf bound_ctrl:1
	v_add_f32_e32 v158, v158, v159
	ds_write_b32 v137, v158 offset:816
	v_add_f32_dpp v155, v155, v155 quad_perm:[2,3,0,1] row_mask:0xf bank_mask:0xf bound_ctrl:1
	s_nop 1
	v_add_f32_dpp v156, v155, v155 row_half_mirror row_mask:0xf bank_mask:0xf bound_ctrl:1
	v_pk_fma_f32 v[126:127], v[156:157], v[32:33], v[126:127] op_sel_hi:[0,1,1]
	v_pk_fma_f32 v[124:125], v[156:157], v[34:35], v[124:125] op_sel_hi:[0,1,1]
	v_pk_fma_f32 v[122:123], v[156:157], v[36:37], v[122:123] op_sel_hi:[0,1,1]
	v_pk_fma_f32 v[120:121], v[156:157], v[38:39], v[120:121] op_sel_hi:[0,1,1]
	ds_read_b128 v[24:27], v154 offset:34560
	ds_read_b128 v[28:31], v154 offset:34576
	ds_read_b128 v[16:19], v154 offset:34304
	ds_read_b128 v[20:23], v154 offset:34320
	ds_read_b128 v[32:35], v154 offset:34816
	ds_read_b128 v[36:39], v154 offset:34832
	ds_read_b32 v116, v153 offset:35072
	s_waitcnt lgkmcnt(7)
; #define LAS __attribute__((address_space(3)))
; DI unsigned pack2(float lo, float hi) { f32x2 v = {lo, hi}; return __builtin_bit_cast(unsigned, __builtin_convertvector(v, bf16x2_t)); }
; DI void scan_item(PP p, int l, int item, LAS unsigned char* lds) {
;     ...
;     for (int c = 0; c < NCH; ++c) {
;         if (wid >= 4) { if (c + 1 < NCH) { fill(c + 1); if (c + 2 < NCH) gl(c + 2); } }
;         else {
;             const LAS float* sp = buf + ((c & 1) * T) * 384;
;             f32x4 Ar0, Ar1, Aw0, Aw1, Ak0, Ak1, Aa0, Aa1, Ab0, Ab1; float Avv;
;             f32x4 Br0, Br1, Bw0, Bw1, Bk0, Bk1, Ba0, Ba1, Bb0, Bb1; float Bvv;
;             SC_LD(A, sp);
;             const ptrdiff_t ystep = dir ? -512 : 512;
;             u16* Yl = Yp + (size_t)steprow(b, dir, c * T) * 512 + (ptrdiff_t)ks * ystep;
; #pragma nounroll
;             for (int st = 0; st < T; st += 2) {
;                 SC_LD(B, sp + (st + 1) * 384);
;                 SC_STEP(A, st);
;                 if (st + 2 < T) SC_LD(A, sp + (st + 2) * 384);
;                 SC_STEP(B, st + 1);
;                 if ((st & 6) == 6) {
;                     const LAS float* rp = ypl + (ks * 68 - lane) + (lane & ~7);
;                     const f32x4 q0 = *(const LAS f32x4*)rp, q1 = *(const LAS f32x4*)(rp + 4);
;                     Yl[(ptrdiff_t)(st - 6) * ystep] = (u16)(pack2(((q0[0] + q0[1]) + (q0[2] + q0[3])) + ((q1[0] + q1[1]) + (q1[2] + q1[3])), 0.f) & 0xffffu);
;                 }
	v_pk_mul_f32 v[156:157], v[64:65], v[126:127]
	v_pk_mul_f32 v[90:91], v[68:69], v[122:123]
	v_pk_mul_f32 v[158:159], v[0:1], v[126:127]
	v_pk_fma_f32 v[156:157], v[124:125], v[66:67], v[156:157]
	v_pk_fma_f32 v[90:91], v[120:121], v[70:71], v[90:91]
	v_pk_fma_f32 v[158:159], v[124:125], v[2:3], v[158:159]
	v_pk_fma_f32 v[126:127], v[128:129], v[56:57], v[126:127] op_sel_hi:[0,1,1]
	v_pk_fma_f32 v[158:159], v[122:123], v[4:5], v[158:159]
	v_pk_fma_f32 v[124:125], v[128:129], v[58:59], v[124:125] op_sel_hi:[0,1,1]
	v_pk_add_f32 v[156:157], v[156:157], v[90:91]
	v_pk_fma_f32 v[158:159], v[120:121], v[6:7], v[158:159]
	v_add_f32_e32 v155, v156, v157
	v_pk_fma_f32 v[122:123], v[128:129], v[60:61], v[122:123] op_sel_hi:[0,1,1]
	v_pk_fma_f32 v[120:121], v[128:129], v[62:63], v[120:121] op_sel_hi:[0,1,1]
	ds_read_b128 v[0:3], v154 offset:33792
	ds_read_b128 v[4:7], v154 offset:33808
	v_add_f32_dpp v155, v155, v155 quad_perm:[1,0,3,2] row_mask:0xf bank_mask:0xf bound_ctrl:1
	v_add_f32_e32 v158, v158, v159
	ds_write_b32 v137, v158 offset:1088
	v_add_f32_dpp v155, v155, v155 quad_perm:[2,3,0,1] row_mask:0xf bank_mask:0xf bound_ctrl:1
	s_nop 1
	v_add_f32_dpp v156, v155, v155 row_half_mirror row_mask:0xf bank_mask:0xf bound_ctrl:1
	v_pk_fma_f32 v[126:127], v[156:157], v[72:73], v[126:127] op_sel_hi:[0,1,1]
	v_pk_fma_f32 v[124:125], v[156:157], v[74:75], v[124:125] op_sel_hi:[0,1,1]
	v_pk_fma_f32 v[122:123], v[156:157], v[76:77], v[122:123] op_sel_hi:[0,1,1]
	v_pk_fma_f32 v[120:121], v[156:157], v[78:79], v[120:121] op_sel_hi:[0,1,1]
	ds_read_b128 v[64:67], v154 offset:36096
	ds_read_b128 v[68:71], v154 offset:36112
	ds_read_b128 v[56:59], v154 offset:35840
	ds_read_b128 v[60:63], v154 offset:35856
	ds_read_b128 v[72:75], v154 offset:36352
	ds_read_b128 v[76:79], v154 offset:36368
	ds_read_b32 v128, v153 offset:36608
	ds_read_b128 v[48:51], v154 offset:35584
	ds_read_b128 v[52:55], v154 offset:35600
	s_waitcnt lgkmcnt(9)
	v_pk_mul_f32 v[156:157], v[24:25], v[126:127]
	v_pk_mul_f32 v[90:91], v[28:29], v[122:123]
	v_pk_mul_f32 v[158:159], v[40:41], v[126:127]
	v_pk_fma_f32 v[156:157], v[124:125], v[26:27], v[156:157]
	v_pk_fma_f32 v[90:91], v[120:121], v[30:31], v[90:91]
	v_pk_fma_f32 v[158:159], v[124:125], v[42:43], v[158:159]
	v_pk_fma_f32 v[126:127], v[116:117], v[16:17], v[126:127] op_sel_hi:[0,1,1]
	v_pk_fma_f32 v[158:159], v[122:123], v[44:45], v[158:159]
	v_pk_fma_f32 v[124:125], v[116:117], v[18:19], v[124:125] op_sel_hi:[0,1,1]
	v_pk_add_f32 v[156:157], v[156:157], v[90:91]
	v_pk_fma_f32 v[158:159], v[120:121], v[46:47], v[158:159]
	v_add_f32_e32 v155, v156, v157
	v_pk_fma_f32 v[122:123], v[116:117], v[20:21], v[122:123] op_sel_hi:[0,1,1]
	v_pk_fma_f32 v[120:121], v[116:117], v[22:23], v[120:121] op_sel_hi:[0,1,1]
	ds_read_b128 v[40:43], v154 offset:35328
	ds_read_b128 v[44:47], v154 offset:35344
	v_add_f32_dpp v155, v155, v155 quad_perm:[1,0,3,2] row_mask:0xf bank_mask:0xf bound_ctrl:1
	v_add_f32_e32 v158, v158, v159
	ds_write_b32 v137, v158 offset:1360
	v_add_f32_dpp v155, v155, v155 quad_perm:[2,3,0,1] row_mask:0xf bank_mask:0xf bound_ctrl:1
	s_nop 1
	v_add_f32_dpp v156, v155, v155 row_half_mirror row_mask:0xf bank_mask:0xf bound_ctrl:1
	v_pk_fma_f32 v[126:127], v[156:157], v[32:33], v[126:127] op_sel_hi:[0,1,1]
	v_pk_fma_f32 v[124:125], v[156:157], v[34:35], v[124:125] op_sel_hi:[0,1,1]
	v_pk_fma_f32 v[122:123], v[156:157], v[36:37], v[122:123] op_sel_hi:[0,1,1]
	v_pk_fma_f32 v[120:121], v[156:157], v[38:39], v[120:121] op_sel_hi:[0,1,1]
	ds_read_b128 v[24:27], v154 offset:37632
	ds_read_b128 v[28:31], v154 offset:37648
	ds_read_b128 v[16:19], v154 offset:37376
	ds_read_b128 v[20:23], v154 offset:37392
	ds_read_b128 v[32:35], v154 offset:37888
	ds_read_b128 v[36:39], v154 offset:37904
	ds_read_b32 v116, v153 offset:38144
	s_waitcnt lgkmcnt(7)
	v_pk_mul_f32 v[156:157], v[64:65], v[126:127]
	v_pk_mul_f32 v[90:91], v[68:69], v[122:123]
	v_pk_mul_f32 v[158:159], v[0:1], v[126:127]
	v_pk_fma_f32 v[156:157], v[124:125], v[66:67], v[156:157]
	v_pk_fma_f32 v[90:91], v[120:121], v[70:71], v[90:91]
	v_pk_fma_f32 v[158:159], v[124:125], v[2:3], v[158:159]
	v_pk_fma_f32 v[126:127], v[128:129], v[56:57], v[126:127] op_sel_hi:[0,1,1]
	v_pk_fma_f32 v[158:159], v[122:123], v[4:5], v[158:159]
	v_pk_fma_f32 v[124:125], v[128:129], v[58:59], v[124:125] op_sel_hi:[0,1,1]
	v_pk_add_f32 v[156:157], v[156:157], v[90:91]
	v_pk_fma_f32 v[158:159], v[120:121], v[6:7], v[158:159]
	v_add_f32_e32 v155, v156, v157
	v_pk_fma_f32 v[122:123], v[128:129], v[60:61], v[122:123] op_sel_hi:[0,1,1]
	v_pk_fma_f32 v[120:121], v[128:129], v[62:63], v[120:121] op_sel_hi:[0,1,1]
	ds_read_b128 v[0:3], v154 offset:36864
	ds_read_b128 v[4:7], v154 offset:36880
	v_add_f32_dpp v155, v155, v155 quad_perm:[1,0,3,2] row_mask:0xf bank_mask:0xf bound_ctrl:1
	v_add_f32_e32 v158, v158, v159
	ds_write_b32 v137, v158 offset:1632
	v_add_f32_dpp v155, v155, v155 quad_perm:[2,3,0,1] row_mask:0xf bank_mask:0xf bound_ctrl:1
	s_nop 1
	v_add_f32_dpp v156, v155, v155 row_half_mirror row_mask:0xf bank_mask:0xf bound_ctrl:1
	v_pk_fma_f32 v[126:127], v[156:157], v[72:73], v[126:127] op_sel_hi:[0,1,1]
	v_pk_fma_f32 v[124:125], v[156:157], v[74:75], v[124:125] op_sel_hi:[0,1,1]
	v_pk_fma_f32 v[122:123], v[156:157], v[76:77], v[122:123] op_sel_hi:[0,1,1]
	v_pk_fma_f32 v[120:121], v[156:157], v[78:79], v[120:121] op_sel_hi:[0,1,1]
	v_pk_mul_f32 v[158:159], v[40:41], v[126:127]
	s_nop 0
	v_pk_fma_f32 v[158:159], v[124:125], v[42:43], v[158:159]
	s_nop 0
	v_pk_fma_f32 v[158:159], v[122:123], v[44:45], v[158:159]
	s_nop 0
	v_pk_fma_f32 v[158:159], v[120:121], v[46:47], v[158:159]
	s_nop 0
	v_add_f32_e32 v158, v158, v159
	ds_write_b32 v137, v158 offset:1904
	ds_read_b128 v[82:85], v139
	ds_read_b128 v[86:89], v139 offset:16
	v_pk_mul_f32 v[126:127], v[48:49], v[126:127]
	v_pk_mul_f32 v[124:125], v[50:51], v[124:125]
	v_pk_mul_f32 v[122:123], v[52:53], v[122:123]
	v_pk_mul_f32 v[120:121], v[54:55], v[120:121]
	ds_read_b128 v[40:43], v154 offset:38400
	ds_read_b128 v[44:47], v154 offset:38416
	ds_read_b128 v[64:67], v154 offset:39168
	ds_read_b128 v[68:71], v154 offset:39184
	ds_read_b128 v[56:59], v154 offset:38912
	ds_read_b128 v[60:63], v154 offset:38928
	ds_read_b128 v[72:75], v154 offset:39424
	ds_read_b128 v[76:79], v154 offset:39440
	ds_read_b32 v128, v153 offset:39680
	s_waitcnt lgkmcnt(9)
; #define LAS __attribute__((address_space(3)))
; DI unsigned pack2(float lo, float hi) { f32x2 v = {lo, hi}; return __builtin_bit_cast(unsigned, __builtin_convertvector(v, bf16x2_t)); }
; DI void scan_item(PP p, int l, int item, LAS unsigned char* lds) {
;     ...
;     for (int c = 0; c < NCH; ++c) {
;         if (wid >= 4) { if (c + 1 < NCH) { fill(c + 1); if (c + 2 < NCH) gl(c + 2); } }
;         else {
;             const LAS float* sp = buf + ((c & 1) * T) * 384;
;             f32x4 Ar0, Ar1, Aw0, Aw1, Ak0, Ak1, Aa0, Aa1, Ab0, Ab1; float Avv;
;             f32x4 Br0, Br1, Bw0, Bw1, Bk0, Bk1, Ba0, Ba1, Bb0, Bb1; float Bvv;
;             SC_LD(A, sp);
;             const ptrdiff_t ystep = dir ? -512 : 512;
;             u16* Yl = Yp + (size_t)steprow(b, dir, c * T) * 512 + (ptrdiff_t)ks * ystep;
; #pragma nounroll
;             for (int st = 0; st < T; st += 2) {
;                 SC_LD(B, sp + (st + 1) * 384);
;                 SC_STEP(A, st);
;                 if (st + 2 < T) SC_LD(A, sp + (st + 2) * 384);
;                 SC_STEP(B, st + 1);
;                 if ((st & 6) == 6) {
;                     const LAS float* rp = ypl + (ks * 68 - lane) + (lane & ~7);
;                     const f32x4 q0 = *(const LAS f32x4*)rp, q1 = *(const LAS f32x4*)(rp + 4);
;                     Yl[(ptrdiff_t)(st - 6) * ystep] = (u16)(pack2(((q0[0] + q0[1]) + (q0[2] + q0[3])) + ((q1[0] + q1[1]) + (q1[2] + q1[3])), 0.f) & 0xffffu);
;                 }
	v_pk_mul_f32 v[156:157], v[24:25], v[126:127]
	v_pk_mul_f32 v[90:91], v[28:29], v[122:123]
	v_pk_fma_f32 v[126:127], v[116:117], v[16:17], v[126:127] op_sel_hi:[0,1,1]
	v_pk_fma_f32 v[156:157], v[124:125], v[26:27], v[156:157]
	v_pk_fma_f32 v[90:91], v[120:121], v[30:31], v[90:91]
	v_pk_fma_f32 v[124:125], v[116:117], v[18:19], v[124:125] op_sel_hi:[0,1,1]
	v_pk_fma_f32 v[122:123], v[116:117], v[20:21], v[122:123] op_sel_hi:[0,1,1]
	v_pk_add_f32 v[156:157], v[156:157], v[90:91]
	v_pk_fma_f32 v[120:121], v[116:117], v[22:23], v[120:121] op_sel_hi:[0,1,1]
	v_add_f32_e32 v155, v156, v157
	s_nop 1
	v_add_f32_dpp v155, v155, v155 quad_perm:[1,0,3,2] row_mask:0xf bank_mask:0xf bound_ctrl:1
	s_nop 1
	v_add_f32_dpp v155, v155, v155 quad_perm:[2,3,0,1] row_mask:0xf bank_mask:0xf bound_ctrl:1
	s_nop 1
	v_add_f32_dpp v156, v155, v155 row_half_mirror row_mask:0xf bank_mask:0xf bound_ctrl:1
	v_pk_fma_f32 v[126:127], v[156:157], v[32:33], v[126:127] op_sel_hi:[0,1,1]
	v_pk_add_f32 v[82:83], v[82:83], v[84:85]
	v_pk_fma_f32 v[124:125], v[156:157], v[34:35], v[124:125] op_sel_hi:[0,1,1]
	v_pk_add_f32 v[86:87], v[86:87], v[88:89]
	v_pk_fma_f32 v[122:123], v[156:157], v[36:37], v[122:123] op_sel_hi:[0,1,1]
	v_pk_add_f32 v[82:83], v[82:83], v[86:87]
	v_pk_fma_f32 v[120:121], v[156:157], v[38:39], v[120:121] op_sel_hi:[0,1,1]
	v_add_f32_e32 v82, v82, v83
	v_cvt_pk_bf16_f32 v82, v82, v82
	global_store_short v[118:119], v82, off
	v_lshl_add_u64 v[118:119], s[8:9], 0, v[118:119]
	ds_read_b128 v[24:27], v154 offset:40704
	ds_read_b128 v[28:31], v154 offset:40720
	ds_read_b128 v[16:19], v154 offset:40448
	ds_read_b128 v[20:23], v154 offset:40464
	ds_read_b128 v[32:35], v154 offset:40960
	ds_read_b128 v[36:39], v154 offset:40976
	ds_read_b32 v116, v153 offset:41216
	s_waitcnt lgkmcnt(7)
	v_pk_mul_f32 v[156:157], v[64:65], v[126:127]
	v_pk_mul_f32 v[90:91], v[68:69], v[122:123]
	v_pk_mul_f32 v[158:159], v[0:1], v[126:127]
	v_pk_fma_f32 v[156:157], v[124:125], v[66:67], v[156:157]
	v_pk_fma_f32 v[90:91], v[120:121], v[70:71], v[90:91]
	v_pk_fma_f32 v[158:159], v[124:125], v[2:3], v[158:159]
	v_pk_fma_f32 v[126:127], v[128:129], v[56:57], v[126:127] op_sel_hi:[0,1,1]
	v_pk_fma_f32 v[158:159], v[122:123], v[4:5], v[158:159]
	v_pk_fma_f32 v[124:125], v[128:129], v[58:59], v[124:125] op_sel_hi:[0,1,1]
	v_pk_add_f32 v[156:157], v[156:157], v[90:91]
	v_pk_fma_f32 v[158:159], v[120:121], v[6:7], v[158:159]
	v_add_f32_e32 v155, v156, v157
	v_pk_fma_f32 v[122:123], v[128:129], v[60:61], v[122:123] op_sel_hi:[0,1,1]
	v_pk_fma_f32 v[120:121], v[128:129], v[62:63], v[120:121] op_sel_hi:[0,1,1]
	ds_read_b128 v[0:3], v154 offset:39936
	ds_read_b128 v[4:7], v154 offset:39952
	v_add_f32_dpp v155, v155, v155 quad_perm:[1,0,3,2] row_mask:0xf bank_mask:0xf bound_ctrl:1
	v_add_f32_e32 v158, v158, v159
	ds_write_b32 v137, v158 offset:0
	v_add_f32_dpp v155, v155, v155 quad_perm:[2,3,0,1] row_mask:0xf bank_mask:0xf bound_ctrl:1
	s_nop 1
	v_add_f32_dpp v156, v155, v155 row_half_mirror row_mask:0xf bank_mask:0xf bound_ctrl:1
	v_pk_fma_f32 v[126:127], v[156:157], v[72:73], v[126:127] op_sel_hi:[0,1,1]
	v_pk_fma_f32 v[124:125], v[156:157], v[74:75], v[124:125] op_sel_hi:[0,1,1]
	v_pk_fma_f32 v[122:123], v[156:157], v[76:77], v[122:123] op_sel_hi:[0,1,1]
	v_pk_fma_f32 v[120:121], v[156:157], v[78:79], v[120:121] op_sel_hi:[0,1,1]
	ds_read_b128 v[64:67], v154 offset:42240
	ds_read_b128 v[68:71], v154 offset:42256
	ds_read_b128 v[56:59], v154 offset:41984
	ds_read_b128 v[60:63], v154 offset:42000
	ds_read_b128 v[72:75], v154 offset:42496
	ds_read_b128 v[76:79], v154 offset:42512
	ds_read_b32 v128, v153 offset:42752
	s_waitcnt lgkmcnt(7)
	v_pk_mul_f32 v[156:157], v[24:25], v[126:127]
	v_pk_mul_f32 v[90:91], v[28:29], v[122:123]
	v_pk_mul_f32 v[158:159], v[40:41], v[126:127]
	v_pk_fma_f32 v[156:157], v[124:125], v[26:27], v[156:157]
	v_pk_fma_f32 v[90:91], v[120:121], v[30:31], v[90:91]
	v_pk_fma_f32 v[158:159], v[124:125], v[42:43], v[158:159]
	v_pk_fma_f32 v[126:127], v[116:117], v[16:17], v[126:127] op_sel_hi:[0,1,1]
	v_pk_fma_f32 v[158:159], v[122:123], v[44:45], v[158:159]
	v_pk_fma_f32 v[124:125], v[116:117], v[18:19], v[124:125] op_sel_hi:[0,1,1]
	v_pk_add_f32 v[156:157], v[156:157], v[90:91]
	v_pk_fma_f32 v[158:159], v[120:121], v[46:47], v[158:159]
	v_add_f32_e32 v155, v156, v157
	v_pk_fma_f32 v[122:123], v[116:117], v[20:21], v[122:123] op_sel_hi:[0,1,1]
	v_pk_fma_f32 v[120:121], v[116:117], v[22:23], v[120:121] op_sel_hi:[0,1,1]
	ds_read_b128 v[40:43], v154 offset:41472
	ds_read_b128 v[44:47], v154 offset:41488
	v_add_f32_dpp v155, v155, v155 quad_perm:[1,0,3,2] row_mask:0xf bank_mask:0xf bound_ctrl:1
	v_add_f32_e32 v158, v158, v159
	ds_write_b32 v137, v158 offset:272
	v_add_f32_dpp v155, v155, v155 quad_perm:[2,3,0,1] row_mask:0xf bank_mask:0xf bound_ctrl:1
	s_nop 1
	v_add_f32_dpp v156, v155, v155 row_half_mirror row_mask:0xf bank_mask:0xf bound_ctrl:1
	v_pk_fma_f32 v[126:127], v[156:157], v[32:33], v[126:127] op_sel_hi:[0,1,1]
	v_pk_fma_f32 v[124:125], v[156:157], v[34:35], v[124:125] op_sel_hi:[0,1,1]
	v_pk_fma_f32 v[122:123], v[156:157], v[36:37], v[122:123] op_sel_hi:[0,1,1]
	v_pk_fma_f32 v[120:121], v[156:157], v[38:39], v[120:121] op_sel_hi:[0,1,1]
	ds_read_b128 v[24:27], v154 offset:43776
	ds_read_b128 v[28:31], v154 offset:43792
	ds_read_b128 v[16:19], v154 offset:43520
	ds_read_b128 v[20:23], v154 offset:43536
	ds_read_b128 v[32:35], v154 offset:44032
	ds_read_b128 v[36:39], v154 offset:44048
	ds_read_b32 v116, v153 offset:44288
	s_waitcnt lgkmcnt(7)
; #define LAS __attribute__((address_space(3)))
; DI unsigned pack2(float lo, float hi) { f32x2 v = {lo, hi}; return __builtin_bit_cast(unsigned, __builtin_convertvector(v, bf16x2_t)); }
; DI void scan_item(PP p, int l, int item, LAS unsigned char* lds) {
;     ...
;     for (int c = 0; c < NCH; ++c) {
;         if (wid >= 4) { if (c + 1 < NCH) { fill(c + 1); if (c + 2 < NCH) gl(c + 2); } }
;         else {
;             const LAS float* sp = buf + ((c & 1) * T) * 384;
;             f32x4 Ar0, Ar1, Aw0, Aw1, Ak0, Ak1, Aa0, Aa1, Ab0, Ab1; float Avv;
;             f32x4 Br0, Br1, Bw0, Bw1, Bk0, Bk1, Ba0, Ba1, Bb0, Bb1; float Bvv;
;             SC_LD(A, sp);
;             const ptrdiff_t ystep = dir ? -512 : 512;
;             u16* Yl = Yp + (size_t)steprow(b, dir, c * T) * 512 + (ptrdiff_t)ks * ystep;
; #pragma nounroll
;             for (int st = 0; st < T; st += 2) {
;                 SC_LD(B, sp + (st + 1) * 384);
;                 SC_STEP(A, st);
;                 if (st + 2 < T) SC_LD(A, sp + (st + 2) * 384);
;                 SC_STEP(B, st + 1);
;                 if ((st & 6) == 6) {
;                     const LAS float* rp = ypl + (ks * 68 - lane) + (lane & ~7);
;                     const f32x4 q0 = *(const LAS f32x4*)rp, q1 = *(const LAS f32x4*)(rp + 4);
;                     Yl[(ptrdiff_t)(st - 6) * ystep] = (u16)(pack2(((q0[0] + q0[1]) + (q0[2] + q0[3])) + ((q1[0] + q1[1]) + (q1[2] + q1[3])), 0.f) & 0xffffu);
;                 }
	v_pk_mul_f32 v[156:157], v[64:65], v[126:127]
	v_pk_mul_f32 v[90:91], v[68:69], v[122:123]
	v_pk_mul_f32 v[158:159], v[0:1], v[126:127]
	v_pk_fma_f32 v[156:157], v[124:125], v[66:67], v[156:157]
	v_pk_fma_f32 v[90:91], v[120:121], v[70:71], v[90:91]
	v_pk_fma_f32 v[158:159], v[124:125], v[2:3], v[158:159]
	v_pk_fma_f32 v[126:127], v[128:129], v[56:57], v[126:127] op_sel_hi:[0,1,1]
	v_pk_fma_f32 v[158:159], v[122:123], v[4:5], v[158:159]
	v_pk_fma_f32 v[124:125], v[128:129], v[58:59], v[124:125] op_sel_hi:[0,1,1]
	v_pk_add_f32 v[156:157], v[156:157], v[90:91]
	v_pk_fma_f32 v[158:159], v[120:121], v[6:7], v[158:159]
	v_add_f32_e32 v155, v156, v157
	v_pk_fma_f32 v[122:123], v[128:129], v[60:61], v[122:123] op_sel_hi:[0,1,1]
	v_pk_fma_f32 v[120:121], v[128:129], v[62:63], v[120:121] op_sel_hi:[0,1,1]
	ds_read_b128 v[0:3], v154 offset:43008
	ds_read_b128 v[4:7], v154 offset:43024
	v_add_f32_dpp v155, v155, v155 quad_perm:[1,0,3,2] row_mask:0xf bank_mask:0xf bound_ctrl:1
	v_add_f32_e32 v158, v158, v159
	ds_write_b32 v137, v158 offset:544
	v_add_f32_dpp v155, v155, v155 quad_perm:[2,3,0,1] row_mask:0xf bank_mask:0xf bound_ctrl:1
	s_nop 1
	v_add_f32_dpp v156, v155, v155 row_half_mirror row_mask:0xf bank_mask:0xf bound_ctrl:1
	v_pk_fma_f32 v[126:127], v[156:157], v[72:73], v[126:127] op_sel_hi:[0,1,1]
	v_pk_fma_f32 v[124:125], v[156:157], v[74:75], v[124:125] op_sel_hi:[0,1,1]
	v_pk_fma_f32 v[122:123], v[156:157], v[76:77], v[122:123] op_sel_hi:[0,1,1]
	v_pk_fma_f32 v[120:121], v[156:157], v[78:79], v[120:121] op_sel_hi:[0,1,1]
	ds_read_b128 v[64:67], v154 offset:45312
	ds_read_b128 v[68:71], v154 offset:45328
	ds_read_b128 v[56:59], v154 offset:45056
	ds_read_b128 v[60:63], v154 offset:45072
	ds_read_b128 v[72:75], v154 offset:45568
	ds_read_b128 v[76:79], v154 offset:45584
	ds_read_b32 v128, v153 offset:45824
	s_waitcnt lgkmcnt(7)
	v_pk_mul_f32 v[156:157], v[24:25], v[126:127]
	v_pk_mul_f32 v[90:91], v[28:29], v[122:123]
	v_pk_mul_f32 v[158:159], v[40:41], v[126:127]
	v_pk_fma_f32 v[156:157], v[124:125], v[26:27], v[156:157]
	v_pk_fma_f32 v[90:91], v[120:121], v[30:31], v[90:91]
	v_pk_fma_f32 v[158:159], v[124:125], v[42:43], v[158:159]
	v_pk_fma_f32 v[126:127], v[116:117], v[16:17], v[126:127] op_sel_hi:[0,1,1]
	v_pk_fma_f32 v[158:159], v[122:123], v[44:45], v[158:159]
	v_pk_fma_f32 v[124:125], v[116:117], v[18:19], v[124:125] op_sel_hi:[0,1,1]
	v_pk_add_f32 v[156:157], v[156:157], v[90:91]
	v_pk_fma_f32 v[158:159], v[120:121], v[46:47], v[158:159]
	v_add_f32_e32 v155, v156, v157
	v_pk_fma_f32 v[122:123], v[116:117], v[20:21], v[122:123] op_sel_hi:[0,1,1]
	v_pk_fma_f32 v[120:121], v[116:117], v[22:23], v[120:121] op_sel_hi:[0,1,1]
	ds_read_b128 v[40:43], v154 offset:44544
	ds_read_b128 v[44:47], v154 offset:44560
	v_add_f32_dpp v155, v155, v155 quad_perm:[1,0,3,2] row_mask:0xf bank_mask:0xf bound_ctrl:1
	v_add_f32_e32 v158, v158, v159
	ds_write_b32 v137, v158 offset:816
	v_add_f32_dpp v155, v155, v155 quad_perm:[2,3,0,1] row_mask:0xf bank_mask:0xf bound_ctrl:1
	s_nop 1
	v_add_f32_dpp v156, v155, v155 row_half_mirror row_mask:0xf bank_mask:0xf bound_ctrl:1
	v_pk_fma_f32 v[126:127], v[156:157], v[32:33], v[126:127] op_sel_hi:[0,1,1]
	v_pk_fma_f32 v[124:125], v[156:157], v[34:35], v[124:125] op_sel_hi:[0,1,1]
	v_pk_fma_f32 v[122:123], v[156:157], v[36:37], v[122:123] op_sel_hi:[0,1,1]
	v_pk_fma_f32 v[120:121], v[156:157], v[38:39], v[120:121] op_sel_hi:[0,1,1]
	ds_read_b128 v[24:27], v154 offset:46848
	ds_read_b128 v[28:31], v154 offset:46864
	ds_read_b128 v[16:19], v154 offset:46592
	ds_read_b128 v[20:23], v154 offset:46608
	ds_read_b128 v[32:35], v154 offset:47104
	ds_read_b128 v[36:39], v154 offset:47120
	ds_read_b32 v116, v153 offset:47360
	s_waitcnt lgkmcnt(7)
	v_pk_mul_f32 v[156:157], v[64:65], v[126:127]
	v_pk_mul_f32 v[90:91], v[68:69], v[122:123]
	v_pk_mul_f32 v[158:159], v[0:1], v[126:127]
	v_pk_fma_f32 v[156:157], v[124:125], v[66:67], v[156:157]
	v_pk_fma_f32 v[90:91], v[120:121], v[70:71], v[90:91]
	v_pk_fma_f32 v[158:159], v[124:125], v[2:3], v[158:159]
	v_pk_fma_f32 v[126:127], v[128:129], v[56:57], v[126:127] op_sel_hi:[0,1,1]
	v_pk_fma_f32 v[158:159], v[122:123], v[4:5], v[158:159]
	v_pk_fma_f32 v[124:125], v[128:129], v[58:59], v[124:125] op_sel_hi:[0,1,1]
	v_pk_add_f32 v[156:157], v[156:157], v[90:91]
	v_pk_fma_f32 v[158:159], v[120:121], v[6:7], v[158:159]
	v_add_f32_e32 v155, v156, v157
	v_pk_fma_f32 v[122:123], v[128:129], v[60:61], v[122:123] op_sel_hi:[0,1,1]
	v_pk_fma_f32 v[120:121], v[128:129], v[62:63], v[120:121] op_sel_hi:[0,1,1]
	ds_read_b128 v[0:3], v154 offset:46080
	ds_read_b128 v[4:7], v154 offset:46096
	v_add_f32_dpp v155, v155, v155 quad_perm:[1,0,3,2] row_mask:0xf bank_mask:0xf bound_ctrl:1
	v_add_f32_e32 v158, v158, v159
	ds_write_b32 v137, v158 offset:1088
	v_add_f32_dpp v155, v155, v155 quad_perm:[2,3,0,1] row_mask:0xf bank_mask:0xf bound_ctrl:1
	s_nop 1
	v_add_f32_dpp v156, v155, v155 row_half_mirror row_mask:0xf bank_mask:0xf bound_ctrl:1
	v_pk_fma_f32 v[126:127], v[156:157], v[72:73], v[126:127] op_sel_hi:[0,1,1]
	v_pk_fma_f32 v[124:125], v[156:157], v[74:75], v[124:125] op_sel_hi:[0,1,1]
	v_pk_fma_f32 v[122:123], v[156:157], v[76:77], v[122:123] op_sel_hi:[0,1,1]
	v_pk_fma_f32 v[120:121], v[156:157], v[78:79], v[120:121] op_sel_hi:[0,1,1]
	ds_read_b128 v[64:67], v154 offset:48384
	ds_read_b128 v[68:71], v154 offset:48400
	ds_read_b128 v[56:59], v154 offset:48128
	ds_read_b128 v[60:63], v154 offset:48144
	ds_read_b128 v[72:75], v154 offset:48640
	ds_read_b128 v[76:79], v154 offset:48656
	ds_read_b32 v128, v153 offset:48896
	ds_read_b128 v[48:51], v154 offset:47872
	ds_read_b128 v[52:55], v154 offset:47888
	s_waitcnt lgkmcnt(9)
; #define LAS __attribute__((address_space(3)))
; DI unsigned pack2(float lo, float hi) { f32x2 v = {lo, hi}; return __builtin_bit_cast(unsigned, __builtin_convertvector(v, bf16x2_t)); }
; DI void scan_item(PP p, int l, int item, LAS unsigned char* lds) {
;     ...
;             for (int st = 0; st < T; st += 2) {
;                 SC_LD(B, sp + (st + 1) * 384);
;                 SC_STEP(A, st);
;                 if (st + 2 < T) SC_LD(A, sp + (st + 2) * 384);
;                 SC_STEP(B, st + 1);
;                 if ((st & 6) == 6) {
;                     const LAS float* rp = ypl + (ks * 68 - lane) + (lane & ~7);
;                     const f32x4 q0 = *(const LAS f32x4*)rp, q1 = *(const LAS f32x4*)(rp + 4);
;                     Yl[(ptrdiff_t)(st - 6) * ystep] = (u16)(pack2(((q0[0] + q0[1]) + (q0[2] + q0[3])) + ((q1[0] + q1[1]) + (q1[2] + q1[3])), 0.f) & 0xffffu);
;                 }
;             }
	v_pk_mul_f32 v[156:157], v[24:25], v[126:127]
	v_pk_mul_f32 v[90:91], v[28:29], v[122:123]
	v_pk_mul_f32 v[158:159], v[40:41], v[126:127]
	v_pk_fma_f32 v[156:157], v[124:125], v[26:27], v[156:157]
	v_pk_fma_f32 v[90:91], v[120:121], v[30:31], v[90:91]
	v_pk_fma_f32 v[158:159], v[124:125], v[42:43], v[158:159]
	v_pk_fma_f32 v[126:127], v[116:117], v[16:17], v[126:127] op_sel_hi:[0,1,1]
	v_pk_fma_f32 v[158:159], v[122:123], v[44:45], v[158:159]
	v_pk_fma_f32 v[124:125], v[116:117], v[18:19], v[124:125] op_sel_hi:[0,1,1]
	v_pk_add_f32 v[156:157], v[156:157], v[90:91]
	v_pk_fma_f32 v[158:159], v[120:121], v[46:47], v[158:159]
	v_add_f32_e32 v155, v156, v157
	v_pk_fma_f32 v[122:123], v[116:117], v[20:21], v[122:123] op_sel_hi:[0,1,1]
	v_pk_fma_f32 v[120:121], v[116:117], v[22:23], v[120:121] op_sel_hi:[0,1,1]
	ds_read_b128 v[40:43], v154 offset:47616
	ds_read_b128 v[44:47], v154 offset:47632
	v_add_f32_dpp v155, v155, v155 quad_perm:[1,0,3,2] row_mask:0xf bank_mask:0xf bound_ctrl:1
	v_add_f32_e32 v158, v158, v159
	ds_write_b32 v137, v158 offset:1360
	v_add_f32_dpp v155, v155, v155 quad_perm:[2,3,0,1] row_mask:0xf bank_mask:0xf bound_ctrl:1
	s_nop 1
	v_add_f32_dpp v156, v155, v155 row_half_mirror row_mask:0xf bank_mask:0xf bound_ctrl:1
	v_pk_fma_f32 v[126:127], v[156:157], v[32:33], v[126:127] op_sel_hi:[0,1,1]
	v_pk_fma_f32 v[124:125], v[156:157], v[34:35], v[124:125] op_sel_hi:[0,1,1]
	v_pk_fma_f32 v[122:123], v[156:157], v[36:37], v[122:123] op_sel_hi:[0,1,1]
	v_pk_fma_f32 v[120:121], v[156:157], v[38:39], v[120:121] op_sel_hi:[0,1,1]
	s_waitcnt lgkmcnt(0)
	v_pk_mul_f32 v[156:157], v[64:65], v[126:127]
	v_pk_mul_f32 v[90:91], v[68:69], v[122:123]
	v_pk_mul_f32 v[158:159], v[0:1], v[126:127]
	v_pk_fma_f32 v[156:157], v[124:125], v[66:67], v[156:157]
	v_pk_fma_f32 v[90:91], v[120:121], v[70:71], v[90:91]
	v_pk_fma_f32 v[158:159], v[124:125], v[2:3], v[158:159]
	v_pk_fma_f32 v[126:127], v[128:129], v[56:57], v[126:127] op_sel_hi:[0,1,1]
	v_pk_fma_f32 v[158:159], v[122:123], v[4:5], v[158:159]
	v_pk_fma_f32 v[124:125], v[128:129], v[58:59], v[124:125] op_sel_hi:[0,1,1]
	v_pk_add_f32 v[156:157], v[156:157], v[90:91]
	v_pk_fma_f32 v[158:159], v[120:121], v[6:7], v[158:159]
	v_add_f32_e32 v155, v156, v157
	v_pk_fma_f32 v[122:123], v[128:129], v[60:61], v[122:123] op_sel_hi:[0,1,1]
	v_pk_fma_f32 v[120:121], v[128:129], v[62:63], v[120:121] op_sel_hi:[0,1,1]
	v_add_f32_dpp v155, v155, v155 quad_perm:[1,0,3,2] row_mask:0xf bank_mask:0xf bound_ctrl:1
	v_add_f32_e32 v158, v158, v159
	ds_write_b32 v137, v158 offset:1632
	v_add_f32_dpp v155, v155, v155 quad_perm:[2,3,0,1] row_mask:0xf bank_mask:0xf bound_ctrl:1
	s_nop 1
	v_add_f32_dpp v156, v155, v155 row_half_mirror row_mask:0xf bank_mask:0xf bound_ctrl:1
	v_pk_fma_f32 v[126:127], v[156:157], v[72:73], v[126:127] op_sel_hi:[0,1,1]
	v_pk_fma_f32 v[124:125], v[156:157], v[74:75], v[124:125] op_sel_hi:[0,1,1]
	v_pk_fma_f32 v[122:123], v[156:157], v[76:77], v[122:123] op_sel_hi:[0,1,1]
	v_pk_fma_f32 v[120:121], v[156:157], v[78:79], v[120:121] op_sel_hi:[0,1,1]
	v_pk_mul_f32 v[158:159], v[40:41], v[126:127]
	s_nop 0
	v_pk_fma_f32 v[158:159], v[124:125], v[42:43], v[158:159]
	s_nop 0
	v_pk_fma_f32 v[158:159], v[122:123], v[44:45], v[158:159]
	s_nop 0
	v_pk_fma_f32 v[158:159], v[120:121], v[46:47], v[158:159]
	s_nop 0
	v_add_f32_e32 v158, v158, v159
	ds_write_b32 v137, v158 offset:1904
	ds_read_b128 v[82:85], v139
	ds_read_b128 v[86:89], v139 offset:16
	v_pk_mul_f32 v[126:127], v[48:49], v[126:127]
	v_pk_mul_f32 v[124:125], v[50:51], v[124:125]
	v_pk_mul_f32 v[122:123], v[52:53], v[122:123]
	v_pk_mul_f32 v[120:121], v[54:55], v[120:121]
	s_waitcnt lgkmcnt(0)
	v_pk_add_f32 v[82:83], v[82:83], v[84:85]
	v_pk_add_f32 v[86:87], v[86:87], v[88:89]
	s_nop 0
	v_pk_add_f32 v[82:83], v[82:83], v[86:87]
	s_nop 0
	v_add_f32_e32 v82, v82, v83
	v_cvt_pk_bf16_f32 v82, v82, v82
	global_store_short v[118:119], v82, off
	s_setprio 0
